# on top of v1: DMAs lead each load segment, ds_reads interleaved behind them
# speedup vs baseline: 1.0039x; 1.0039x over previous
; #define PG8_STAGE(bufoff, gbase, voff) do { _Pragma("unroll") for (int _i = 0; _i < 2; ++_i) \
;         __builtin_amdgcn_global_load_lds((const unsigned*)((const char*)(gbase) + (voff)[_i]), (PG8_LAS unsigned*)(lds + (bufoff) + ldsw + _i * 8192), 16, 0, 0); } while (0)
; #define PG8_LDA(dst, b, h) do { _Pragma("unroll") for (int m = 0; m < 4; ++m) _Pragma("unroll") for (int k = 0; k < 2; ++k) dst[m][k] = *(const PG8_LAS bf16x8*)(lds + PG8_SA(b, h) + aoff + m * 2048 + k * 1024); } while (0)
; #define PG8_LDB(dst, b, h) do { _Pragma("unroll") for (int n = 0; n < 2; ++n) _Pragma("unroll") for (int k = 0; k < 2; ++k) dst[n][k] = *(const PG8_LAS bf16x8*)(lds + PG8_SB(b, h) + boff + n * 2048 + k * 1024); } while (0)
; #define PG8_MMA(ai, bj, At, Bt) do { __builtin_amdgcn_s_setprio(1); _Pragma("unroll") for (int m = 0; m < 4; ++m) _Pragma("unroll") for (int n = 0; n < 2; ++n) _Pragma("unroll") for (int k = 0; k < 2; ++k) \
;         acc[ai][bj][m][n] = __builtin_amdgcn_mfma_f32_16x16x32_bf16(Bt[n][k], At[m][k], acc[ai][bj][m][n], 0, 0, 0); __builtin_amdgcn_s_setprio(0); } while (0)
; #define PG8_WAIT_V(n) asm volatile("s_waitcnt vmcnt(" #n ")" ::: "memory")
; #define PG8_BAR __builtin_amdgcn_s_barrier()
; template <class Epi, class Sched, bool ALIGN_EPI = false, bool SP2 = false>
; __device__ __forceinline__ void gemm_phase(PG8_LAS unsigned char* lds, const Gemm g, const Sched& S, const Epi& E, const int wave_id) {
;     ...
;         for (int t = 0; t < nt; t += 2) {
;             const bool last = (t == nt - 2);
;             const char* a1 = cA + (size_t)(t + 1) * kstep;
;             const char* a2 = last ? nA : cA + (size_t)(t + 2) * kstep; const char* b2 = last ? nB : cB + (size_t)(t + 2) * kstep;
;             const char* a3 = a2 + kstep; const char* b3 = b2 + kstep;
;             if (last && has_next) S.a_ready(nxt);
;             if constexpr (SP2) {
;             PG8_LDB(B0, 0, 0); PG8_LDB(B1, 0, 1); PG8_SCHED; PG8_LDA(At, 0, 0); PG8_STAGE(PG8_SA(1, 1), a1 + hstep, voffA);
;             PG8_WAIT_V(8); PG8_WAIT_L(0); PG8_BAR; PG8_MMA(0, 0, At, B0); PG8_MMA(0, 1, At, B1); PG8_BAR; PG8_SCHED;
;             PG8_LDA(At, 0, 1); PG8_STAGE(PG8_SB(0, 0), b2, voffB); PG8_STAGE(PG8_SB(0, 1), b2 + hstep, voffB); PG8_STAGE(PG8_SA(0, 0), a2, voffA);
;             PG8_WAIT_V(8); PG8_WAIT_L(0); PG8_BAR; PG8_MMA(1, 0, At, B0); PG8_MMA(1, 1, At, B1); PG8_BAR; PG8_SCHED;
.LBB0_174:
	s_add_u32 s42, s20, 0xfff80080
	s_addc_u32 s43, s21, -1
	s_add_i32 s76, 0, 0x10000
	s_cmp_eq_u32 s75, 28
	s_cselect_b32 s45, s15, s43
	s_cselect_b32 s44, s41, s42
	s_cselect_b32 s43, s13, s74
	s_cselect_b32 s42, s72, s73
	s_add_i32 s79, 0, 0x14000
	s_add_i32 m0, s56, 0xc000
	s_nop 0
	global_load_lds_dwordx4 v138, s[20:21]
	ds_read_b128 v[142:145], v230
	ds_read_b128 v[146:149], v230 offset:1024
	ds_read_b128 v[150:153], v230 offset:2048
	ds_read_b128 v[154:157], v230 offset:3072
	ds_read_b128 v[158:161], v230 offset:16384
	ds_read_b128 v[162:165], v230 offset:17408
	ds_read_b128 v[166:169], v230 offset:18432
	ds_read_b128 v[178:181], v230 offset:19456
	s_add_i32 m0, s56, 0xe000
	s_nop 0
	global_load_lds_dwordx4 v140, s[20:21]
	ds_read_b128 v[182:185], v175
	ds_read_b128 v[186:189], v175 offset:1024
	ds_read_b128 v[190:193], v175 offset:2048
	ds_read_b128 v[206:209], v175 offset:3072
	ds_read_b128 v[210:213], v175 offset:4096
	ds_read_b128 v[214:217], v175 offset:5120
	ds_read_b128 v[226:229], v175 offset:6144
	ds_read_b128 v[234:237], v175 offset:7168
	s_waitcnt vmcnt(8)
	s_waitcnt lgkmcnt(0)
	s_barrier
	s_setprio 1
	s_waitcnt lgkmcnt(0)
	v_mfma_f32_16x16x32_bf16 v[126:129], v[142:145], v[182:185], v[126:129]
	v_mfma_f32_16x16x32_bf16 v[118:121], v[150:153], v[182:185], v[118:121]
	v_mfma_f32_16x16x32_bf16 v[110:113], v[142:145], v[190:193], v[110:113]
	v_mfma_f32_16x16x32_bf16 v[102:105], v[150:153], v[190:193], v[102:105]
	v_mfma_f32_16x16x32_bf16 v[94:97], v[142:145], v[210:213], v[94:97]
	v_mfma_f32_16x16x32_bf16 v[86:89], v[150:153], v[210:213], v[86:89]
	v_mfma_f32_16x16x32_bf16 v[78:81], v[142:145], v[226:229], v[78:81]
	v_mfma_f32_16x16x32_bf16 v[70:73], v[150:153], v[226:229], v[70:73]
	v_mfma_f32_16x16x32_bf16 v[126:129], v[146:149], v[186:189], v[126:129]
	v_mfma_f32_16x16x32_bf16 v[118:121], v[154:157], v[186:189], v[118:121]
	v_mfma_f32_16x16x32_bf16 v[110:113], v[146:149], v[206:209], v[110:113]
	v_mfma_f32_16x16x32_bf16 v[102:105], v[154:157], v[206:209], v[102:105]
	v_mfma_f32_16x16x32_bf16 v[94:97], v[146:149], v[214:217], v[94:97]
	v_mfma_f32_16x16x32_bf16 v[86:89], v[154:157], v[214:217], v[86:89]
	v_mfma_f32_16x16x32_bf16 v[78:81], v[146:149], v[234:237], v[78:81]
	v_mfma_f32_16x16x32_bf16 v[70:73], v[154:157], v[234:237], v[70:73]
	s_setprio 0
	s_setprio 1
	v_mfma_f32_16x16x32_bf16 v[122:125], v[158:161], v[182:185], v[122:125]
	v_mfma_f32_16x16x32_bf16 v[114:117], v[166:169], v[182:185], v[114:117]
	v_mfma_f32_16x16x32_bf16 v[106:109], v[158:161], v[190:193], v[106:109]
	v_mfma_f32_16x16x32_bf16 v[98:101], v[166:169], v[190:193], v[98:101]
	v_mfma_f32_16x16x32_bf16 v[90:93], v[158:161], v[210:213], v[90:93]
	v_mfma_f32_16x16x32_bf16 v[82:85], v[166:169], v[210:213], v[82:85]
	v_mfma_f32_16x16x32_bf16 v[74:77], v[158:161], v[226:229], v[74:77]
	v_mfma_f32_16x16x32_bf16 v[66:69], v[166:169], v[226:229], v[66:69]
	v_mfma_f32_16x16x32_bf16 v[122:125], v[162:165], v[186:189], v[122:125]
	v_mfma_f32_16x16x32_bf16 v[114:117], v[178:181], v[186:189], v[114:117]
	v_mfma_f32_16x16x32_bf16 v[106:109], v[162:165], v[206:209], v[106:109]
	v_mfma_f32_16x16x32_bf16 v[98:101], v[178:181], v[206:209], v[98:101]
	v_mfma_f32_16x16x32_bf16 v[90:93], v[162:165], v[214:217], v[90:93]
	v_mfma_f32_16x16x32_bf16 v[82:85], v[178:181], v[214:217], v[82:85]
	v_mfma_f32_16x16x32_bf16 v[74:77], v[162:165], v[234:237], v[74:77]
	v_mfma_f32_16x16x32_bf16 v[66:69], v[178:181], v[234:237], v[66:69]
	s_setprio 0
	s_barrier
	s_add_i32 s76, s76, s53
	s_mov_b32 m0, s76
	s_nop 0
	global_load_lds_dwordx4 v132, s[42:43]
	ds_read_b128 v[182:185], v175 offset:16384
	ds_read_b128 v[186:189], v175 offset:17408
	s_add_i32 m0, s76, 0x2000
	s_add_u32 s76, s42, 0x80000
	s_addc_u32 s77, s43, 0
	s_add_i32 s79, s79, s53
	global_load_lds_dwordx4 v136, s[42:43]
	ds_read_b128 v[190:193], v175 offset:18432
	ds_read_b128 v[206:209], v175 offset:19456
	s_mov_b32 m0, s79
	s_nop 0
	global_load_lds_dwordx4 v132, s[76:77]
	ds_read_b128 v[210:213], v175 offset:20480
	ds_read_b128 v[214:217], v175 offset:21504
	s_add_i32 m0, s79, 0x2000
	s_nop 0
	global_load_lds_dwordx4 v136, s[76:77]
	ds_read_b128 v[226:229], v175 offset:22528
	ds_read_b128 v[234:237], v175 offset:23552
	s_mov_b32 m0, s56
	s_nop 0
	global_load_lds_dwordx4 v130, s[44:45]
	s_mov_b32 m0, s57
	s_nop 0
	global_load_lds_dwordx4 v134, s[44:45]
	s_waitcnt vmcnt(8)
	s_waitcnt lgkmcnt(0)
	s_barrier
	s_setprio 1
	s_waitcnt lgkmcnt(0)
	v_mfma_f32_16x16x32_bf16 v[62:65], v[142:145], v[182:185], v[62:65]
	v_mfma_f32_16x16x32_bf16 v[54:57], v[150:153], v[182:185], v[54:57]
	v_mfma_f32_16x16x32_bf16 v[46:49], v[142:145], v[190:193], v[46:49]
	v_mfma_f32_16x16x32_bf16 v[38:41], v[150:153], v[190:193], v[38:41]
	v_mfma_f32_16x16x32_bf16 v[30:33], v[142:145], v[210:213], v[30:33]
	v_mfma_f32_16x16x32_bf16 v[22:25], v[150:153], v[210:213], v[22:25]
	v_mfma_f32_16x16x32_bf16 v[14:17], v[142:145], v[226:229], v[14:17]
	v_mfma_f32_16x16x32_bf16 v[6:9], v[150:153], v[226:229], v[6:9]
	v_mfma_f32_16x16x32_bf16 v[62:65], v[146:149], v[186:189], v[62:65]
	v_mfma_f32_16x16x32_bf16 v[54:57], v[154:157], v[186:189], v[54:57]
	v_mfma_f32_16x16x32_bf16 v[46:49], v[146:149], v[206:209], v[46:49]
	v_mfma_f32_16x16x32_bf16 v[38:41], v[154:157], v[206:209], v[38:41]
	v_mfma_f32_16x16x32_bf16 v[30:33], v[146:149], v[214:217], v[30:33]
	v_mfma_f32_16x16x32_bf16 v[22:25], v[154:157], v[214:217], v[22:25]
	v_mfma_f32_16x16x32_bf16 v[14:17], v[146:149], v[234:237], v[14:17]
	v_mfma_f32_16x16x32_bf16 v[6:9], v[154:157], v[234:237], v[6:9]
	s_setprio 0
	s_setprio 1
	v_mfma_f32_16x16x32_bf16 v[58:61], v[158:161], v[182:185], v[58:61]
	v_mfma_f32_16x16x32_bf16 v[50:53], v[166:169], v[182:185], v[50:53]
	v_mfma_f32_16x16x32_bf16 v[42:45], v[158:161], v[190:193], v[42:45]
	v_mfma_f32_16x16x32_bf16 v[34:37], v[166:169], v[190:193], v[34:37]
	v_mfma_f32_16x16x32_bf16 v[26:29], v[158:161], v[210:213], v[26:29]
	v_mfma_f32_16x16x32_bf16 v[18:21], v[166:169], v[210:213], v[18:21]
	v_mfma_f32_16x16x32_bf16 v[10:13], v[158:161], v[226:229], v[10:13]
	v_mfma_f32_16x16x32_bf16 v[2:5], v[166:169], v[226:229], v[2:5]
	v_mfma_f32_16x16x32_bf16 v[58:61], v[162:165], v[186:189], v[58:61]
	v_mfma_f32_16x16x32_bf16 v[50:53], v[178:181], v[186:189], v[50:53]
	v_mfma_f32_16x16x32_bf16 v[42:45], v[162:165], v[206:209], v[42:45]
	v_mfma_f32_16x16x32_bf16 v[34:37], v[178:181], v[206:209], v[34:37]
	v_mfma_f32_16x16x32_bf16 v[26:29], v[162:165], v[214:217], v[26:29]
	v_mfma_f32_16x16x32_bf16 v[18:21], v[178:181], v[214:217], v[18:21]
	v_mfma_f32_16x16x32_bf16 v[10:13], v[162:165], v[234:237], v[10:13]
	v_mfma_f32_16x16x32_bf16 v[2:5], v[178:181], v[234:237], v[2:5]
	s_setprio 0
	s_barrier
; #define PG8_STAGE(bufoff, gbase, voff) do { _Pragma("unroll") for (int _i = 0; _i < 2; ++_i) \
;         __builtin_amdgcn_global_load_lds((const unsigned*)((const char*)(gbase) + (voff)[_i]), (PG8_LAS unsigned*)(lds + (bufoff) + ldsw + _i * 8192), 16, 0, 0); } while (0)
; #define PG8_LDA(dst, b, h) do { _Pragma("unroll") for (int m = 0; m < 4; ++m) _Pragma("unroll") for (int k = 0; k < 2; ++k) dst[m][k] = *(const PG8_LAS bf16x8*)(lds + PG8_SA(b, h) + aoff + m * 2048 + k * 1024); } while (0)
; #define PG8_LDB(dst, b, h) do { _Pragma("unroll") for (int n = 0; n < 2; ++n) _Pragma("unroll") for (int k = 0; k < 2; ++k) dst[n][k] = *(const PG8_LAS bf16x8*)(lds + PG8_SB(b, h) + boff + n * 2048 + k * 1024); } while (0)
; #define PG8_MMA(ai, bj, At, Bt) do { __builtin_amdgcn_s_setprio(1); _Pragma("unroll") for (int m = 0; m < 4; ++m) _Pragma("unroll") for (int n = 0; n < 2; ++n) _Pragma("unroll") for (int k = 0; k < 2; ++k) \
;         acc[ai][bj][m][n] = __builtin_amdgcn_mfma_f32_16x16x32_bf16(Bt[n][k], At[m][k], acc[ai][bj][m][n], 0, 0, 0); __builtin_amdgcn_s_setprio(0); } while (0)
; #define PG8_WAIT_V(n) asm volatile("s_waitcnt vmcnt(" #n ")" ::: "memory")
; #define PG8_WAIT_L(n) asm volatile("s_waitcnt lgkmcnt(" #n ")" ::: "memory")
; #define PG8_BAR __builtin_amdgcn_s_barrier()
; #define PG8_SCHED __builtin_amdgcn_sched_barrier(0)
; template <class Epi, class Sched, bool ALIGN_EPI = false, bool SP2 = false>
; __device__ __forceinline__ void gemm_phase(PG8_LAS unsigned char* lds, const Gemm g, const Sched& S, const Epi& E, const int wave_id) {
;     ...
;             PG8_LDB(B0, 1, 0); PG8_LDB(B1, 1, 1); PG8_SCHED; PG8_LDA(At, 1, 0); PG8_STAGE(PG8_SA(0, 1), a2 + hstep, voffA);
;             PG8_WAIT_V(8); PG8_WAIT_L(0); PG8_BAR; PG8_MMA(0, 0, At, B0); PG8_MMA(0, 1, At, B1); PG8_BAR; PG8_SCHED;
;             PG8_LDA(At, 1, 1); PG8_STAGE(PG8_SB(1, 0), b3, voffB); PG8_STAGE(PG8_SB(1, 1), b3 + hstep, voffB); PG8_STAGE(PG8_SA(1, 0), a3, voffA);
;             PG8_WAIT_V(8); PG8_WAIT_L(0); PG8_BAR; PG8_MMA(1, 0, At, B0); PG8_MMA(1, 1, At, B1); PG8_BAR; PG8_SCHED;
;     ...
;         if constexpr (ALIGN_EPI) { if (wr == 0) PG8_BAR; }
	s_add_i32 s76, 0, 0x18000
	s_add_i32 s77, 0, 0x1c000
	s_add_u32 s44, s44, 0x80000
	s_addc_u32 s45, s45, 0
	s_mov_b32 m0, s64
	s_nop 0
	global_load_lds_dwordx4 v130, s[44:45]
	ds_read_b128 v[142:145], v230 offset:32768
	ds_read_b128 v[146:149], v230 offset:33792
	ds_read_b128 v[150:153], v230 offset:34816
	ds_read_b128 v[154:157], v230 offset:35840
	ds_read_b128 v[158:161], v230 offset:49152
	ds_read_b128 v[162:165], v230 offset:50176
	ds_read_b128 v[166:169], v230 offset:51200
	ds_read_b128 v[178:181], v230 offset:52224
	s_mov_b32 m0, s65
	s_nop 0
	global_load_lds_dwordx4 v134, s[44:45]
	ds_read_b128 v[182:185], v175 offset:32768
	ds_read_b128 v[186:189], v175 offset:33792
	ds_read_b128 v[190:193], v175 offset:34816
	ds_read_b128 v[206:209], v175 offset:35840
	ds_read_b128 v[210:213], v175 offset:36864
	ds_read_b128 v[214:217], v175 offset:37888
	ds_read_b128 v[226:229], v175 offset:38912
	ds_read_b128 v[234:237], v175 offset:39936
	s_waitcnt vmcnt(8)
	s_waitcnt lgkmcnt(0)
	s_barrier
	s_setprio 1
	s_waitcnt lgkmcnt(0)
	v_mfma_f32_16x16x32_bf16 v[126:129], v[142:145], v[182:185], v[126:129]
	v_mfma_f32_16x16x32_bf16 v[118:121], v[150:153], v[182:185], v[118:121]
	v_mfma_f32_16x16x32_bf16 v[110:113], v[142:145], v[190:193], v[110:113]
	v_mfma_f32_16x16x32_bf16 v[102:105], v[150:153], v[190:193], v[102:105]
	v_mfma_f32_16x16x32_bf16 v[94:97], v[142:145], v[210:213], v[94:97]
	v_mfma_f32_16x16x32_bf16 v[86:89], v[150:153], v[210:213], v[86:89]
	v_mfma_f32_16x16x32_bf16 v[78:81], v[142:145], v[226:229], v[78:81]
	v_mfma_f32_16x16x32_bf16 v[70:73], v[150:153], v[226:229], v[70:73]
	v_mfma_f32_16x16x32_bf16 v[126:129], v[146:149], v[186:189], v[126:129]
	v_mfma_f32_16x16x32_bf16 v[118:121], v[154:157], v[186:189], v[118:121]
	v_mfma_f32_16x16x32_bf16 v[110:113], v[146:149], v[206:209], v[110:113]
	v_mfma_f32_16x16x32_bf16 v[102:105], v[154:157], v[206:209], v[102:105]
	v_mfma_f32_16x16x32_bf16 v[94:97], v[146:149], v[214:217], v[94:97]
	v_mfma_f32_16x16x32_bf16 v[86:89], v[154:157], v[214:217], v[86:89]
	v_mfma_f32_16x16x32_bf16 v[78:81], v[146:149], v[234:237], v[78:81]
	v_mfma_f32_16x16x32_bf16 v[70:73], v[154:157], v[234:237], v[70:73]
	s_setprio 0
	s_setprio 1
	v_mfma_f32_16x16x32_bf16 v[122:125], v[158:161], v[182:185], v[122:125]
	v_mfma_f32_16x16x32_bf16 v[114:117], v[166:169], v[182:185], v[114:117]
	v_mfma_f32_16x16x32_bf16 v[106:109], v[158:161], v[190:193], v[106:109]
	v_mfma_f32_16x16x32_bf16 v[98:101], v[166:169], v[190:193], v[98:101]
	v_mfma_f32_16x16x32_bf16 v[90:93], v[158:161], v[210:213], v[90:93]
	v_mfma_f32_16x16x32_bf16 v[82:85], v[166:169], v[210:213], v[82:85]
	v_mfma_f32_16x16x32_bf16 v[74:77], v[158:161], v[226:229], v[74:77]
	v_mfma_f32_16x16x32_bf16 v[66:69], v[166:169], v[226:229], v[66:69]
	v_mfma_f32_16x16x32_bf16 v[122:125], v[162:165], v[186:189], v[122:125]
	v_mfma_f32_16x16x32_bf16 v[114:117], v[178:181], v[186:189], v[114:117]
	v_mfma_f32_16x16x32_bf16 v[106:109], v[162:165], v[206:209], v[106:109]
	v_mfma_f32_16x16x32_bf16 v[98:101], v[178:181], v[206:209], v[98:101]
	v_mfma_f32_16x16x32_bf16 v[90:93], v[162:165], v[214:217], v[90:93]
	v_mfma_f32_16x16x32_bf16 v[82:85], v[178:181], v[214:217], v[82:85]
	v_mfma_f32_16x16x32_bf16 v[74:77], v[162:165], v[234:237], v[74:77]
	v_mfma_f32_16x16x32_bf16 v[66:69], v[178:181], v[234:237], v[66:69]
	s_setprio 0
	s_barrier
	s_add_u32 vcc_lo, s44, 0xfff80080
	s_addc_u32 vcc_hi, s45, -1
	s_mov_b32 m0, s68
	s_nop 0
	global_load_lds_dwordx4 v130, vcc
	ds_read_b128 v[182:185], v175 offset:49152
	ds_read_b128 v[186:189], v175 offset:50176
	s_mov_b32 m0, s69
	s_add_i32 s44, s76, s53
	global_load_lds_dwordx4 v134, vcc
	ds_read_b128 v[190:193], v175 offset:51200
	ds_read_b128 v[206:209], v175 offset:52224
	s_add_u32 vcc_lo, s42, 0x80
	s_addc_u32 vcc_hi, s43, 0
	s_mov_b32 m0, s44
	s_nop 0
	global_load_lds_dwordx4 v132, vcc
	ds_read_b128 v[210:213], v175 offset:53248
	ds_read_b128 v[214:217], v175 offset:54272
	s_add_i32 m0, s44, 0x2000
	s_add_u32 s42, s42, 0x80080
	s_addc_u32 s43, s43, 0
	global_load_lds_dwordx4 v136, vcc
	ds_read_b128 v[226:229], v175 offset:55296
	ds_read_b128 v[234:237], v175 offset:56320
	s_add_i32 s44, s77, s53
	s_mov_b32 m0, s44
	s_nop 0
	global_load_lds_dwordx4 v132, s[42:43]
	s_add_i32 m0, s44, 0x2000
	s_nop 0
	global_load_lds_dwordx4 v136, s[42:43]
	s_waitcnt vmcnt(8)
	s_waitcnt lgkmcnt(0)
	s_barrier
	s_setprio 1
	s_waitcnt lgkmcnt(0)
	v_mfma_f32_16x16x32_bf16 v[62:65], v[142:145], v[182:185], v[62:65]
	v_mfma_f32_16x16x32_bf16 v[54:57], v[150:153], v[182:185], v[54:57]
	v_mfma_f32_16x16x32_bf16 v[46:49], v[142:145], v[190:193], v[46:49]
	v_mfma_f32_16x16x32_bf16 v[38:41], v[150:153], v[190:193], v[38:41]
	v_mfma_f32_16x16x32_bf16 v[30:33], v[142:145], v[210:213], v[30:33]
	v_mfma_f32_16x16x32_bf16 v[22:25], v[150:153], v[210:213], v[22:25]
	v_mfma_f32_16x16x32_bf16 v[14:17], v[142:145], v[226:229], v[14:17]
	v_mfma_f32_16x16x32_bf16 v[6:9], v[150:153], v[226:229], v[6:9]
	v_mfma_f32_16x16x32_bf16 v[62:65], v[146:149], v[186:189], v[62:65]
	v_mfma_f32_16x16x32_bf16 v[54:57], v[154:157], v[186:189], v[54:57]
	v_mfma_f32_16x16x32_bf16 v[46:49], v[146:149], v[206:209], v[46:49]
	v_mfma_f32_16x16x32_bf16 v[38:41], v[154:157], v[206:209], v[38:41]
	v_mfma_f32_16x16x32_bf16 v[30:33], v[146:149], v[214:217], v[30:33]
	v_mfma_f32_16x16x32_bf16 v[22:25], v[154:157], v[214:217], v[22:25]
	v_mfma_f32_16x16x32_bf16 v[14:17], v[146:149], v[234:237], v[14:17]
	v_mfma_f32_16x16x32_bf16 v[6:9], v[154:157], v[234:237], v[6:9]
	s_setprio 0
	s_setprio 1
	v_mfma_f32_16x16x32_bf16 v[58:61], v[158:161], v[182:185], v[58:61]
	v_mfma_f32_16x16x32_bf16 v[50:53], v[166:169], v[182:185], v[50:53]
	v_mfma_f32_16x16x32_bf16 v[42:45], v[158:161], v[190:193], v[42:45]
	v_mfma_f32_16x16x32_bf16 v[34:37], v[166:169], v[190:193], v[34:37]
	v_mfma_f32_16x16x32_bf16 v[26:29], v[158:161], v[210:213], v[26:29]
	v_mfma_f32_16x16x32_bf16 v[18:21], v[166:169], v[210:213], v[18:21]
	v_mfma_f32_16x16x32_bf16 v[10:13], v[158:161], v[226:229], v[10:13]
	v_mfma_f32_16x16x32_bf16 v[2:5], v[166:169], v[226:229], v[2:5]
	v_mfma_f32_16x16x32_bf16 v[58:61], v[162:165], v[186:189], v[58:61]
	v_mfma_f32_16x16x32_bf16 v[50:53], v[178:181], v[186:189], v[50:53]
	v_mfma_f32_16x16x32_bf16 v[42:45], v[162:165], v[206:209], v[42:45]
	v_mfma_f32_16x16x32_bf16 v[34:37], v[178:181], v[206:209], v[34:37]
	v_mfma_f32_16x16x32_bf16 v[26:29], v[162:165], v[214:217], v[26:29]
	v_mfma_f32_16x16x32_bf16 v[18:21], v[178:181], v[214:217], v[18:21]
	v_mfma_f32_16x16x32_bf16 v[10:13], v[162:165], v[234:237], v[10:13]
	v_mfma_f32_16x16x32_bf16 v[2:5], v[178:181], v[234:237], v[2:5]
	s_setprio 0
	s_barrier
	s_add_i32 s75, s75, 2
	s_add_u32 s20, s20, 0x100
	s_addc_u32 s21, s21, 0
	s_add_u32 s73, s73, 0x100
	s_addc_u32 s74, s74, 0
	s_cmp_gt_u32 s75, 29
	s_cbranch_scc0 .LBB0_174
	s_and_b64 vcc, exec, s[10:11]
	s_cbranch_vccz .LBB0_177
	s_barrier

; #define PG8_STAGE(bufoff, gbase, voff) do { _Pragma("unroll") for (int _i = 0; _i < 2; ++_i) \
;         __builtin_amdgcn_global_load_lds((const unsigned*)((const char*)(gbase) + (voff)[_i]), (PG8_LAS unsigned*)(lds + (bufoff) + ldsw + _i * 8192), 16, 0, 0); } while (0)
; #define PG8_LDA(dst, b, h) do { _Pragma("unroll") for (int m = 0; m < 4; ++m) _Pragma("unroll") for (int k = 0; k < 2; ++k) dst[m][k] = *(const PG8_LAS bf16x8*)(lds + PG8_SA(b, h) + aoff + m * 2048 + k * 1024); } while (0)
; #define PG8_LDB(dst, b, h) do { _Pragma("unroll") for (int n = 0; n < 2; ++n) _Pragma("unroll") for (int k = 0; k < 2; ++k) dst[n][k] = *(const PG8_LAS bf16x8*)(lds + PG8_SB(b, h) + boff + n * 2048 + k * 1024); } while (0)
; #define PG8_MMA(ai, bj, At, Bt) do { __builtin_amdgcn_s_setprio(1); _Pragma("unroll") for (int m = 0; m < 4; ++m) _Pragma("unroll") for (int n = 0; n < 2; ++n) _Pragma("unroll") for (int k = 0; k < 2; ++k) \
;         acc[ai][bj][m][n] = __builtin_amdgcn_mfma_f32_16x16x32_bf16(Bt[n][k], At[m][k], acc[ai][bj][m][n], 0, 0, 0); __builtin_amdgcn_s_setprio(0); } while (0)
; #define PG8_WAIT_V(n) asm volatile("s_waitcnt vmcnt(" #n ")" ::: "memory")
; #define PG8_BAR __builtin_amdgcn_s_barrier()
; template <class Epi, class Sched, bool ALIGN_EPI = false, bool SP2 = false>
; __device__ __forceinline__ void gemm_phase(PG8_LAS unsigned char* lds, const Gemm g, const Sched& S, const Epi& E, const int wave_id) {
;     ...
;         for (int t = 0; t < nt; t += 2) {
;             const bool last = (t == nt - 2);
;             const char* a1 = cA + (size_t)(t + 1) * kstep;
;             const char* a2 = last ? nA : cA + (size_t)(t + 2) * kstep; const char* b2 = last ? nB : cB + (size_t)(t + 2) * kstep;
;             const char* a3 = a2 + kstep; const char* b3 = b2 + kstep;
;             if (last && has_next) S.a_ready(nxt);
;             if constexpr (SP2) {
;             PG8_LDB(B0, 0, 0); PG8_LDB(B1, 0, 1); PG8_SCHED; PG8_LDA(At, 0, 0); PG8_STAGE(PG8_SA(1, 1), a1 + hstep, voffA);
;             PG8_WAIT_V(8); PG8_WAIT_L(0); PG8_BAR; PG8_MMA(0, 0, At, B0); PG8_MMA(0, 1, At, B1); PG8_BAR; PG8_SCHED;
;             PG8_LDA(At, 0, 1); PG8_STAGE(PG8_SB(0, 0), b2, voffB); PG8_STAGE(PG8_SB(0, 1), b2 + hstep, voffB); PG8_STAGE(PG8_SA(0, 0), a2, voffA);
;             PG8_WAIT_V(8); PG8_WAIT_L(0); PG8_BAR; PG8_MMA(1, 0, At, B0); PG8_MMA(1, 1, At, B1); PG8_BAR; PG8_SCHED;
.LBB0_524:
	s_add_u32 s42, s40, 0xfff80080
	s_addc_u32 s43, s41, -1
	s_add_i32 s77, 0, 0x10000
	s_cmp_eq_u32 s76, 28
	s_cselect_b32 s45, s15, s43
	s_cselect_b32 s44, s21, s42
	s_cselect_b32 s43, s13, s75
	s_cselect_b32 s42, s73, s74
	s_add_i32 s79, 0, 0x14000
	s_add_i32 m0, s56, 0xc000
	s_nop 0
	global_load_lds_dwordx4 v210, s[40:41]
	ds_read_b128 v[118:121], v226
	ds_read_b128 v[122:125], v226 offset:1024
	ds_read_b128 v[130:133], v226 offset:2048
	ds_read_b128 v[134:137], v226 offset:3072
	ds_read_b128 v[146:149], v226 offset:16384
	ds_read_b128 v[150:153], v226 offset:17408
	ds_read_b128 v[154:157], v226 offset:18432
	ds_read_b128 v[158:161], v226 offset:19456
	s_add_i32 m0, s56, 0xe000
	s_nop 0
	global_load_lds_dwordx4 v212, s[40:41]
	ds_read_b128 v[162:165], v222
	ds_read_b128 v[166:169], v222 offset:1024
	ds_read_b128 v[170:173], v222 offset:2048
	ds_read_b128 v[174:177], v222 offset:3072
	ds_read_b128 v[178:181], v222 offset:4096
	ds_read_b128 v[182:185], v222 offset:5120
	ds_read_b128 v[186:189], v222 offset:6144
	ds_read_b128 v[214:217], v222 offset:7168
	s_waitcnt vmcnt(8)
	s_waitcnt lgkmcnt(0)
	s_barrier
	s_setprio 1
	s_waitcnt lgkmcnt(0)
	v_mfma_f32_16x16x32_bf16 v[142:145], v[118:121], v[162:165], v[142:145]
	v_mfma_f32_16x16x32_bf16 v[138:141], v[130:133], v[162:165], v[138:141]
	v_mfma_f32_16x16x32_bf16 v[110:113], v[118:121], v[170:173], v[110:113]
	v_mfma_f32_16x16x32_bf16 v[106:109], v[130:133], v[170:173], v[106:109]
	v_mfma_f32_16x16x32_bf16 v[94:97], v[118:121], v[178:181], v[94:97]
	v_mfma_f32_16x16x32_bf16 v[90:93], v[130:133], v[178:181], v[90:93]
	v_mfma_f32_16x16x32_bf16 v[78:81], v[118:121], v[186:189], v[78:81]
	v_mfma_f32_16x16x32_bf16 v[74:77], v[130:133], v[186:189], v[74:77]
	v_mfma_f32_16x16x32_bf16 v[142:145], v[122:125], v[166:169], v[142:145]
	v_mfma_f32_16x16x32_bf16 v[138:141], v[134:137], v[166:169], v[138:141]
	v_mfma_f32_16x16x32_bf16 v[110:113], v[122:125], v[174:177], v[110:113]
	v_mfma_f32_16x16x32_bf16 v[106:109], v[134:137], v[174:177], v[106:109]
	v_mfma_f32_16x16x32_bf16 v[94:97], v[122:125], v[182:185], v[94:97]
	v_mfma_f32_16x16x32_bf16 v[90:93], v[134:137], v[182:185], v[90:93]
	v_mfma_f32_16x16x32_bf16 v[78:81], v[122:125], v[214:217], v[78:81]
	v_mfma_f32_16x16x32_bf16 v[74:77], v[134:137], v[214:217], v[74:77]
	s_setprio 0
	s_setprio 1
	v_mfma_f32_16x16x32_bf16 v[126:129], v[146:149], v[162:165], v[126:129]
	v_mfma_f32_16x16x32_bf16 v[114:117], v[154:157], v[162:165], v[114:117]
	v_mfma_f32_16x16x32_bf16 v[102:105], v[146:149], v[170:173], v[102:105]
	v_mfma_f32_16x16x32_bf16 v[98:101], v[154:157], v[170:173], v[98:101]
	v_mfma_f32_16x16x32_bf16 v[86:89], v[146:149], v[178:181], v[86:89]
	v_mfma_f32_16x16x32_bf16 v[82:85], v[154:157], v[178:181], v[82:85]
	v_mfma_f32_16x16x32_bf16 v[70:73], v[146:149], v[186:189], v[70:73]
	v_mfma_f32_16x16x32_bf16 v[66:69], v[154:157], v[186:189], v[66:69]
	v_mfma_f32_16x16x32_bf16 v[126:129], v[150:153], v[166:169], v[126:129]
	v_mfma_f32_16x16x32_bf16 v[114:117], v[158:161], v[166:169], v[114:117]
	v_mfma_f32_16x16x32_bf16 v[102:105], v[150:153], v[174:177], v[102:105]
	v_mfma_f32_16x16x32_bf16 v[98:101], v[158:161], v[174:177], v[98:101]
	v_mfma_f32_16x16x32_bf16 v[86:89], v[150:153], v[182:185], v[86:89]
	v_mfma_f32_16x16x32_bf16 v[82:85], v[158:161], v[182:185], v[82:85]
	v_mfma_f32_16x16x32_bf16 v[70:73], v[150:153], v[214:217], v[70:73]
	v_mfma_f32_16x16x32_bf16 v[66:69], v[158:161], v[214:217], v[66:69]
	s_setprio 0
	s_barrier
	s_add_i32 s77, s77, s53
	s_mov_b32 m0, s77
	s_nop 0
	global_load_lds_dwordx4 v192, s[42:43]
	ds_read_b128 v[162:165], v222 offset:16384
	ds_read_b128 v[166:169], v222 offset:17408
	s_add_i32 m0, s77, 0x2000
	s_add_u32 s80, s42, 0x80000
	s_addc_u32 s81, s43, 0
	s_add_i32 s77, s79, s53
	global_load_lds_dwordx4 v208, s[42:43]
	ds_read_b128 v[170:173], v222 offset:18432
	ds_read_b128 v[174:177], v222 offset:19456
	s_mov_b32 m0, s77
	s_nop 0
	global_load_lds_dwordx4 v192, s[80:81]
	ds_read_b128 v[178:181], v222 offset:20480
	ds_read_b128 v[182:185], v222 offset:21504
	s_add_i32 m0, s77, 0x2000
	s_nop 0
	global_load_lds_dwordx4 v208, s[80:81]
	ds_read_b128 v[186:189], v222 offset:22528
	ds_read_b128 v[214:217], v222 offset:23552
	s_mov_b32 m0, s56
	s_nop 0
	global_load_lds_dwordx4 v190, s[44:45]
	s_mov_b32 m0, s57
	s_nop 0
	global_load_lds_dwordx4 v206, s[44:45]
	s_waitcnt vmcnt(8)
	s_waitcnt lgkmcnt(0)
	s_barrier
	s_setprio 1
	s_waitcnt lgkmcnt(0)
	v_mfma_f32_16x16x32_bf16 v[62:65], v[118:121], v[162:165], v[62:65]
	v_mfma_f32_16x16x32_bf16 v[58:61], v[130:133], v[162:165], v[58:61]
	v_mfma_f32_16x16x32_bf16 v[46:49], v[118:121], v[170:173], v[46:49]
	v_mfma_f32_16x16x32_bf16 v[42:45], v[130:133], v[170:173], v[42:45]
	v_mfma_f32_16x16x32_bf16 v[30:33], v[118:121], v[178:181], v[30:33]
	v_mfma_f32_16x16x32_bf16 v[26:29], v[130:133], v[178:181], v[26:29]
	v_mfma_f32_16x16x32_bf16 v[14:17], v[118:121], v[186:189], v[14:17]
	v_mfma_f32_16x16x32_bf16 v[10:13], v[130:133], v[186:189], v[10:13]
	v_mfma_f32_16x16x32_bf16 v[62:65], v[122:125], v[166:169], v[62:65]
	v_mfma_f32_16x16x32_bf16 v[58:61], v[134:137], v[166:169], v[58:61]
	v_mfma_f32_16x16x32_bf16 v[46:49], v[122:125], v[174:177], v[46:49]
	v_mfma_f32_16x16x32_bf16 v[42:45], v[134:137], v[174:177], v[42:45]
	v_mfma_f32_16x16x32_bf16 v[30:33], v[122:125], v[182:185], v[30:33]
	v_mfma_f32_16x16x32_bf16 v[26:29], v[134:137], v[182:185], v[26:29]
	v_mfma_f32_16x16x32_bf16 v[14:17], v[122:125], v[214:217], v[14:17]
	v_mfma_f32_16x16x32_bf16 v[10:13], v[134:137], v[214:217], v[10:13]
	s_setprio 0
	s_setprio 1
	v_mfma_f32_16x16x32_bf16 v[54:57], v[146:149], v[162:165], v[54:57]
	v_mfma_f32_16x16x32_bf16 v[50:53], v[154:157], v[162:165], v[50:53]
	v_mfma_f32_16x16x32_bf16 v[38:41], v[146:149], v[170:173], v[38:41]
	v_mfma_f32_16x16x32_bf16 v[34:37], v[154:157], v[170:173], v[34:37]
	v_mfma_f32_16x16x32_bf16 v[22:25], v[146:149], v[178:181], v[22:25]
	v_mfma_f32_16x16x32_bf16 v[18:21], v[154:157], v[178:181], v[18:21]
	v_mfma_f32_16x16x32_bf16 v[6:9], v[146:149], v[186:189], v[6:9]
	v_mfma_f32_16x16x32_bf16 v[2:5], v[154:157], v[186:189], v[2:5]
	v_mfma_f32_16x16x32_bf16 v[54:57], v[150:153], v[166:169], v[54:57]
	v_mfma_f32_16x16x32_bf16 v[50:53], v[158:161], v[166:169], v[50:53]
	v_mfma_f32_16x16x32_bf16 v[38:41], v[150:153], v[174:177], v[38:41]
	v_mfma_f32_16x16x32_bf16 v[34:37], v[158:161], v[174:177], v[34:37]
	v_mfma_f32_16x16x32_bf16 v[22:25], v[150:153], v[182:185], v[22:25]
	v_mfma_f32_16x16x32_bf16 v[18:21], v[158:161], v[182:185], v[18:21]
	v_mfma_f32_16x16x32_bf16 v[6:9], v[150:153], v[214:217], v[6:9]
	v_mfma_f32_16x16x32_bf16 v[2:5], v[158:161], v[214:217], v[2:5]
	s_setprio 0
	s_barrier
; #define PG8_STAGE(bufoff, gbase, voff) do { _Pragma("unroll") for (int _i = 0; _i < 2; ++_i) \
;         __builtin_amdgcn_global_load_lds((const unsigned*)((const char*)(gbase) + (voff)[_i]), (PG8_LAS unsigned*)(lds + (bufoff) + ldsw + _i * 8192), 16, 0, 0); } while (0)
; #define PG8_LDA(dst, b, h) do { _Pragma("unroll") for (int m = 0; m < 4; ++m) _Pragma("unroll") for (int k = 0; k < 2; ++k) dst[m][k] = *(const PG8_LAS bf16x8*)(lds + PG8_SA(b, h) + aoff + m * 2048 + k * 1024); } while (0)
; #define PG8_LDB(dst, b, h) do { _Pragma("unroll") for (int n = 0; n < 2; ++n) _Pragma("unroll") for (int k = 0; k < 2; ++k) dst[n][k] = *(const PG8_LAS bf16x8*)(lds + PG8_SB(b, h) + boff + n * 2048 + k * 1024); } while (0)
; #define PG8_MMA(ai, bj, At, Bt) do { __builtin_amdgcn_s_setprio(1); _Pragma("unroll") for (int m = 0; m < 4; ++m) _Pragma("unroll") for (int n = 0; n < 2; ++n) _Pragma("unroll") for (int k = 0; k < 2; ++k) \
;         acc[ai][bj][m][n] = __builtin_amdgcn_mfma_f32_16x16x32_bf16(Bt[n][k], At[m][k], acc[ai][bj][m][n], 0, 0, 0); __builtin_amdgcn_s_setprio(0); } while (0)
; #define PG8_WAIT_V(n) asm volatile("s_waitcnt vmcnt(" #n ")" ::: "memory")
; #define PG8_WAIT_L(n) asm volatile("s_waitcnt lgkmcnt(" #n ")" ::: "memory")
; #define PG8_BAR __builtin_amdgcn_s_barrier()
; #define PG8_SCHED __builtin_amdgcn_sched_barrier(0)
; template <class Epi, class Sched, bool ALIGN_EPI = false, bool SP2 = false>
; __device__ __forceinline__ void gemm_phase(PG8_LAS unsigned char* lds, const Gemm g, const Sched& S, const Epi& E, const int wave_id) {
;     ...
;             PG8_LDB(B0, 1, 0); PG8_LDB(B1, 1, 1); PG8_SCHED; PG8_LDA(At, 1, 0); PG8_STAGE(PG8_SA(0, 1), a2 + hstep, voffA);
;             PG8_WAIT_V(8); PG8_WAIT_L(0); PG8_BAR; PG8_MMA(0, 0, At, B0); PG8_MMA(0, 1, At, B1); PG8_BAR; PG8_SCHED;
;             PG8_LDA(At, 1, 1); PG8_STAGE(PG8_SB(1, 0), b3, voffB); PG8_STAGE(PG8_SB(1, 1), b3 + hstep, voffB); PG8_STAGE(PG8_SA(1, 0), a3, voffA);
;             PG8_WAIT_V(8); PG8_WAIT_L(0); PG8_BAR; PG8_MMA(1, 0, At, B0); PG8_MMA(1, 1, At, B1); PG8_BAR; PG8_SCHED;
;     ...
;         if constexpr (ALIGN_EPI) { if (wr == 0) PG8_BAR; }
	s_add_i32 s77, 0, 0x18000
	s_add_i32 s79, 0, 0x1c000
	s_add_u32 s44, s44, 0x80000
	s_addc_u32 s45, s45, 0
	s_mov_b32 m0, s64
	s_nop 0
	global_load_lds_dwordx4 v190, s[44:45]
	ds_read_b128 v[118:121], v226 offset:32768
	ds_read_b128 v[122:125], v226 offset:33792
	ds_read_b128 v[130:133], v226 offset:34816
	ds_read_b128 v[134:137], v226 offset:35840
	ds_read_b128 v[146:149], v226 offset:49152
	ds_read_b128 v[150:153], v226 offset:50176
	ds_read_b128 v[154:157], v226 offset:51200
	ds_read_b128 v[158:161], v226 offset:52224
	s_mov_b32 m0, s65
	s_nop 0
	global_load_lds_dwordx4 v206, s[44:45]
	ds_read_b128 v[162:165], v222 offset:32768
	ds_read_b128 v[166:169], v222 offset:33792
	ds_read_b128 v[170:173], v222 offset:34816
	ds_read_b128 v[174:177], v222 offset:35840
	ds_read_b128 v[178:181], v222 offset:36864
	ds_read_b128 v[182:185], v222 offset:37888
	ds_read_b128 v[186:189], v222 offset:38912
	ds_read_b128 v[214:217], v222 offset:39936
	s_waitcnt vmcnt(8)
	s_waitcnt lgkmcnt(0)
	s_barrier
	s_setprio 1
	s_waitcnt lgkmcnt(0)
	v_mfma_f32_16x16x32_bf16 v[142:145], v[118:121], v[162:165], v[142:145]
	v_mfma_f32_16x16x32_bf16 v[138:141], v[130:133], v[162:165], v[138:141]
	v_mfma_f32_16x16x32_bf16 v[110:113], v[118:121], v[170:173], v[110:113]
	v_mfma_f32_16x16x32_bf16 v[106:109], v[130:133], v[170:173], v[106:109]
	v_mfma_f32_16x16x32_bf16 v[94:97], v[118:121], v[178:181], v[94:97]
	v_mfma_f32_16x16x32_bf16 v[90:93], v[130:133], v[178:181], v[90:93]
	v_mfma_f32_16x16x32_bf16 v[78:81], v[118:121], v[186:189], v[78:81]
	v_mfma_f32_16x16x32_bf16 v[74:77], v[130:133], v[186:189], v[74:77]
	v_mfma_f32_16x16x32_bf16 v[142:145], v[122:125], v[166:169], v[142:145]
	v_mfma_f32_16x16x32_bf16 v[138:141], v[134:137], v[166:169], v[138:141]
	v_mfma_f32_16x16x32_bf16 v[110:113], v[122:125], v[174:177], v[110:113]
	v_mfma_f32_16x16x32_bf16 v[106:109], v[134:137], v[174:177], v[106:109]
	v_mfma_f32_16x16x32_bf16 v[94:97], v[122:125], v[182:185], v[94:97]
	v_mfma_f32_16x16x32_bf16 v[90:93], v[134:137], v[182:185], v[90:93]
	v_mfma_f32_16x16x32_bf16 v[78:81], v[122:125], v[214:217], v[78:81]
	v_mfma_f32_16x16x32_bf16 v[74:77], v[134:137], v[214:217], v[74:77]
	s_setprio 0
	s_setprio 1
	v_mfma_f32_16x16x32_bf16 v[126:129], v[146:149], v[162:165], v[126:129]
	v_mfma_f32_16x16x32_bf16 v[114:117], v[154:157], v[162:165], v[114:117]
	v_mfma_f32_16x16x32_bf16 v[102:105], v[146:149], v[170:173], v[102:105]
	v_mfma_f32_16x16x32_bf16 v[98:101], v[154:157], v[170:173], v[98:101]
	v_mfma_f32_16x16x32_bf16 v[86:89], v[146:149], v[178:181], v[86:89]
	v_mfma_f32_16x16x32_bf16 v[82:85], v[154:157], v[178:181], v[82:85]
	v_mfma_f32_16x16x32_bf16 v[70:73], v[146:149], v[186:189], v[70:73]
	v_mfma_f32_16x16x32_bf16 v[66:69], v[154:157], v[186:189], v[66:69]
	v_mfma_f32_16x16x32_bf16 v[126:129], v[150:153], v[166:169], v[126:129]
	v_mfma_f32_16x16x32_bf16 v[114:117], v[158:161], v[166:169], v[114:117]
	v_mfma_f32_16x16x32_bf16 v[102:105], v[150:153], v[174:177], v[102:105]
	v_mfma_f32_16x16x32_bf16 v[98:101], v[158:161], v[174:177], v[98:101]
	v_mfma_f32_16x16x32_bf16 v[86:89], v[150:153], v[182:185], v[86:89]
	v_mfma_f32_16x16x32_bf16 v[82:85], v[158:161], v[182:185], v[82:85]
	v_mfma_f32_16x16x32_bf16 v[70:73], v[150:153], v[214:217], v[70:73]
	v_mfma_f32_16x16x32_bf16 v[66:69], v[158:161], v[214:217], v[66:69]
	s_setprio 0
	s_barrier
	s_add_u32 vcc_lo, s44, 0xfff80080
	s_addc_u32 vcc_hi, s45, -1
	s_mov_b32 m0, s70
	s_nop 0
	global_load_lds_dwordx4 v190, vcc
	ds_read_b128 v[162:165], v222 offset:49152
	ds_read_b128 v[166:169], v222 offset:50176
	s_mov_b32 m0, s71
	s_add_i32 s44, s77, s53
	global_load_lds_dwordx4 v206, vcc
	ds_read_b128 v[170:173], v222 offset:51200
	ds_read_b128 v[174:177], v222 offset:52224
	s_add_u32 vcc_lo, s42, 0x80
	s_addc_u32 vcc_hi, s43, 0
	s_mov_b32 m0, s44
	s_nop 0
	global_load_lds_dwordx4 v192, vcc
	ds_read_b128 v[178:181], v222 offset:53248
	ds_read_b128 v[182:185], v222 offset:54272
	s_add_i32 m0, s44, 0x2000
	s_add_u32 s42, s42, 0x80080
	s_addc_u32 s43, s43, 0
	global_load_lds_dwordx4 v208, vcc
	ds_read_b128 v[186:189], v222 offset:55296
	ds_read_b128 v[214:217], v222 offset:56320
	s_add_i32 s44, s79, s53
	s_mov_b32 m0, s44
	s_nop 0
	global_load_lds_dwordx4 v192, s[42:43]
	s_add_i32 m0, s44, 0x2000
	s_nop 0
	global_load_lds_dwordx4 v208, s[42:43]
	s_waitcnt vmcnt(8)
	s_waitcnt lgkmcnt(0)
	s_barrier
	s_setprio 1
	s_waitcnt lgkmcnt(0)
	v_mfma_f32_16x16x32_bf16 v[62:65], v[118:121], v[162:165], v[62:65]
	v_mfma_f32_16x16x32_bf16 v[58:61], v[130:133], v[162:165], v[58:61]
	v_mfma_f32_16x16x32_bf16 v[46:49], v[118:121], v[170:173], v[46:49]
	v_mfma_f32_16x16x32_bf16 v[42:45], v[130:133], v[170:173], v[42:45]
	v_mfma_f32_16x16x32_bf16 v[30:33], v[118:121], v[178:181], v[30:33]
	v_mfma_f32_16x16x32_bf16 v[26:29], v[130:133], v[178:181], v[26:29]
	v_mfma_f32_16x16x32_bf16 v[14:17], v[118:121], v[186:189], v[14:17]
	v_mfma_f32_16x16x32_bf16 v[10:13], v[130:133], v[186:189], v[10:13]
	v_mfma_f32_16x16x32_bf16 v[62:65], v[122:125], v[166:169], v[62:65]
	v_mfma_f32_16x16x32_bf16 v[58:61], v[134:137], v[166:169], v[58:61]
	v_mfma_f32_16x16x32_bf16 v[46:49], v[122:125], v[174:177], v[46:49]
	v_mfma_f32_16x16x32_bf16 v[42:45], v[134:137], v[174:177], v[42:45]
	v_mfma_f32_16x16x32_bf16 v[30:33], v[122:125], v[182:185], v[30:33]
	v_mfma_f32_16x16x32_bf16 v[26:29], v[134:137], v[182:185], v[26:29]
	v_mfma_f32_16x16x32_bf16 v[14:17], v[122:125], v[214:217], v[14:17]
	v_mfma_f32_16x16x32_bf16 v[10:13], v[134:137], v[214:217], v[10:13]
	s_setprio 0
	s_setprio 1
	v_mfma_f32_16x16x32_bf16 v[54:57], v[146:149], v[162:165], v[54:57]
	v_mfma_f32_16x16x32_bf16 v[50:53], v[154:157], v[162:165], v[50:53]
	v_mfma_f32_16x16x32_bf16 v[38:41], v[146:149], v[170:173], v[38:41]
	v_mfma_f32_16x16x32_bf16 v[34:37], v[154:157], v[170:173], v[34:37]
	v_mfma_f32_16x16x32_bf16 v[22:25], v[146:149], v[178:181], v[22:25]
	v_mfma_f32_16x16x32_bf16 v[18:21], v[154:157], v[178:181], v[18:21]
	v_mfma_f32_16x16x32_bf16 v[6:9], v[146:149], v[186:189], v[6:9]
	v_mfma_f32_16x16x32_bf16 v[2:5], v[154:157], v[186:189], v[2:5]
	v_mfma_f32_16x16x32_bf16 v[54:57], v[150:153], v[166:169], v[54:57]
	v_mfma_f32_16x16x32_bf16 v[50:53], v[158:161], v[166:169], v[50:53]
	v_mfma_f32_16x16x32_bf16 v[38:41], v[150:153], v[174:177], v[38:41]
	v_mfma_f32_16x16x32_bf16 v[34:37], v[158:161], v[174:177], v[34:37]
	v_mfma_f32_16x16x32_bf16 v[22:25], v[150:153], v[182:185], v[22:25]
	v_mfma_f32_16x16x32_bf16 v[18:21], v[158:161], v[182:185], v[18:21]
	v_mfma_f32_16x16x32_bf16 v[6:9], v[150:153], v[214:217], v[6:9]
	v_mfma_f32_16x16x32_bf16 v[2:5], v[158:161], v[214:217], v[2:5]
	s_setprio 0
	s_barrier
	s_add_i32 s76, s76, 2
	s_add_u32 s40, s40, 0x100
	s_addc_u32 s41, s41, 0
	s_add_u32 s74, s74, 0x100
	s_addc_u32 s75, s75, 0
	s_cmp_gt_u32 s76, 29
	s_cbranch_scc0 .LBB0_524
	s_and_b64 vcc, exec, s[10:11]
	s_cbranch_vccz .LBB0_527
	s_barrier

; #define PG8_STAGE(bufoff, gbase, voff) do { _Pragma("unroll") for (int _i = 0; _i < 2; ++_i) \
;         __builtin_amdgcn_global_load_lds((const unsigned*)((const char*)(gbase) + (voff)[_i]), (PG8_LAS unsigned*)(lds + (bufoff) + ldsw + _i * 8192), 16, 0, 0); } while (0)
; #define PG8_LDA(dst, b, h) do { _Pragma("unroll") for (int m = 0; m < 4; ++m) _Pragma("unroll") for (int k = 0; k < 2; ++k) dst[m][k] = *(const PG8_LAS bf16x8*)(lds + PG8_SA(b, h) + aoff + m * 2048 + k * 1024); } while (0)
; #define PG8_LDB(dst, b, h) do { _Pragma("unroll") for (int n = 0; n < 2; ++n) _Pragma("unroll") for (int k = 0; k < 2; ++k) dst[n][k] = *(const PG8_LAS bf16x8*)(lds + PG8_SB(b, h) + boff + n * 2048 + k * 1024); } while (0)
; #define PG8_MMA(ai, bj, At, Bt) do { __builtin_amdgcn_s_setprio(1); _Pragma("unroll") for (int m = 0; m < 4; ++m) _Pragma("unroll") for (int n = 0; n < 2; ++n) _Pragma("unroll") for (int k = 0; k < 2; ++k) \
;         acc[ai][bj][m][n] = __builtin_amdgcn_mfma_f32_16x16x32_bf16(Bt[n][k], At[m][k], acc[ai][bj][m][n], 0, 0, 0); __builtin_amdgcn_s_setprio(0); } while (0)
; #define PG8_WAIT_V(n) asm volatile("s_waitcnt vmcnt(" #n ")" ::: "memory")
; #define PG8_BAR __builtin_amdgcn_s_barrier()
; template <class Epi, class Sched, bool ALIGN_EPI = false, bool SP2 = false>
; __device__ __forceinline__ void gemm_phase(PG8_LAS unsigned char* lds, const Gemm g, const Sched& S, const Epi& E, const int wave_id) {
;     ...
;         for (int t = 0; t < nt; t += 2) {
;             const bool last = (t == nt - 2);
;             const char* a1 = cA + (size_t)(t + 1) * kstep;
;             const char* a2 = last ? nA : cA + (size_t)(t + 2) * kstep; const char* b2 = last ? nB : cB + (size_t)(t + 2) * kstep;
;             const char* a3 = a2 + kstep; const char* b3 = b2 + kstep;
;             if (last && has_next) S.a_ready(nxt);
;             if constexpr (SP2) {
;             PG8_LDB(B0, 0, 0); PG8_LDB(B1, 0, 1); PG8_SCHED; PG8_LDA(At, 0, 0); PG8_STAGE(PG8_SA(1, 1), a1 + hstep, voffA);
;             PG8_WAIT_V(8); PG8_WAIT_L(0); PG8_BAR; PG8_MMA(0, 0, At, B0); PG8_MMA(0, 1, At, B1); PG8_BAR; PG8_SCHED;
;             PG8_LDA(At, 0, 1); PG8_STAGE(PG8_SB(0, 0), b2, voffB); PG8_STAGE(PG8_SB(0, 1), b2 + hstep, voffB); PG8_STAGE(PG8_SA(0, 0), a2, voffA);
;             PG8_WAIT_V(8); PG8_WAIT_L(0); PG8_BAR; PG8_MMA(1, 0, At, B0); PG8_MMA(1, 1, At, B1); PG8_BAR; PG8_SCHED;
.LBB0_641:
	s_add_u32 s42, s20, 0xfff80080
	s_addc_u32 s43, s21, -1
	s_add_i32 s76, 0, 0x10000
	s_cmp_eq_u32 s75, 28
	s_cselect_b32 s45, s15, s43
	s_cselect_b32 s44, s71, s42
	s_cselect_b32 s43, s13, s74
	s_cselect_b32 s42, s72, s73
	s_add_i32 s79, 0, 0x14000
	s_add_i32 m0, s53, 0xc000
	s_nop 0
	global_load_lds_dwordx4 v138, s[20:21]
	ds_read_b128 v[158:161], v144
	ds_read_b128 v[162:165], v144 offset:1024
	ds_read_b128 v[166:169], v144 offset:2048
	ds_read_b128 v[170:173], v144 offset:3072
	ds_read_b128 v[174:177], v144 offset:16384
	ds_read_b128 v[178:181], v144 offset:17408
	ds_read_b128 v[182:185], v144 offset:18432
	ds_read_b128 v[186:189], v144 offset:19456
	s_add_i32 m0, s53, 0xe000
	s_nop 0
	global_load_lds_dwordx4 v140, s[20:21]
	ds_read_b128 v[190:193], v155
	ds_read_b128 v[206:209], v155 offset:1024
	ds_read_b128 v[210:213], v155 offset:2048
	ds_read_b128 v[214:217], v155 offset:3072
	ds_read_b128 v[226:229], v155 offset:4096
	ds_read_b128 v[234:237], v155 offset:5120
	ds_read_b128 v[238:241], v155 offset:6144
	ds_read_b128 v[242:245], v155 offset:7168
	s_waitcnt vmcnt(8)
	s_waitcnt lgkmcnt(0)
	s_barrier
	s_setprio 1
	s_waitcnt lgkmcnt(0)
	v_mfma_f32_16x16x32_bf16 v[126:129], v[158:161], v[190:193], v[126:129]
	v_mfma_f32_16x16x32_bf16 v[118:121], v[166:169], v[190:193], v[118:121]
	v_mfma_f32_16x16x32_bf16 v[110:113], v[158:161], v[210:213], v[110:113]
	v_mfma_f32_16x16x32_bf16 v[102:105], v[166:169], v[210:213], v[102:105]
	v_mfma_f32_16x16x32_bf16 v[94:97], v[158:161], v[226:229], v[94:97]
	v_mfma_f32_16x16x32_bf16 v[86:89], v[166:169], v[226:229], v[86:89]
	v_mfma_f32_16x16x32_bf16 v[78:81], v[158:161], v[238:241], v[78:81]
	v_mfma_f32_16x16x32_bf16 v[70:73], v[166:169], v[238:241], v[70:73]
	v_mfma_f32_16x16x32_bf16 v[126:129], v[162:165], v[206:209], v[126:129]
	v_mfma_f32_16x16x32_bf16 v[118:121], v[170:173], v[206:209], v[118:121]
	v_mfma_f32_16x16x32_bf16 v[110:113], v[162:165], v[214:217], v[110:113]
	v_mfma_f32_16x16x32_bf16 v[102:105], v[170:173], v[214:217], v[102:105]
	v_mfma_f32_16x16x32_bf16 v[94:97], v[162:165], v[234:237], v[94:97]
	v_mfma_f32_16x16x32_bf16 v[86:89], v[170:173], v[234:237], v[86:89]
	v_mfma_f32_16x16x32_bf16 v[78:81], v[162:165], v[242:245], v[78:81]
	v_mfma_f32_16x16x32_bf16 v[70:73], v[170:173], v[242:245], v[70:73]
	s_setprio 0
	s_setprio 1
	v_mfma_f32_16x16x32_bf16 v[122:125], v[174:177], v[190:193], v[122:125]
	v_mfma_f32_16x16x32_bf16 v[114:117], v[182:185], v[190:193], v[114:117]
	v_mfma_f32_16x16x32_bf16 v[106:109], v[174:177], v[210:213], v[106:109]
	v_mfma_f32_16x16x32_bf16 v[98:101], v[182:185], v[210:213], v[98:101]
	v_mfma_f32_16x16x32_bf16 v[90:93], v[174:177], v[226:229], v[90:93]
	v_mfma_f32_16x16x32_bf16 v[82:85], v[182:185], v[226:229], v[82:85]
	v_mfma_f32_16x16x32_bf16 v[74:77], v[174:177], v[238:241], v[74:77]
	v_mfma_f32_16x16x32_bf16 v[66:69], v[182:185], v[238:241], v[66:69]
	v_mfma_f32_16x16x32_bf16 v[122:125], v[178:181], v[206:209], v[122:125]
	v_mfma_f32_16x16x32_bf16 v[114:117], v[186:189], v[206:209], v[114:117]
	v_mfma_f32_16x16x32_bf16 v[106:109], v[178:181], v[214:217], v[106:109]
	v_mfma_f32_16x16x32_bf16 v[98:101], v[186:189], v[214:217], v[98:101]
	v_mfma_f32_16x16x32_bf16 v[90:93], v[178:181], v[234:237], v[90:93]
	v_mfma_f32_16x16x32_bf16 v[82:85], v[186:189], v[234:237], v[82:85]
	v_mfma_f32_16x16x32_bf16 v[74:77], v[178:181], v[242:245], v[74:77]
	v_mfma_f32_16x16x32_bf16 v[66:69], v[186:189], v[242:245], v[66:69]
	s_setprio 0
	s_barrier
	s_add_i32 s76, s76, s41
	s_mov_b32 m0, s76
	s_nop 0
	global_load_lds_dwordx4 v132, s[42:43]
	ds_read_b128 v[190:193], v155 offset:16384
	ds_read_b128 v[206:209], v155 offset:17408
	s_add_i32 m0, s76, 0x2000
	s_add_u32 s76, s42, 0x80000
	s_addc_u32 s77, s43, 0
	s_add_i32 s79, s79, s41
	global_load_lds_dwordx4 v136, s[42:43]
	ds_read_b128 v[210:213], v155 offset:18432
	ds_read_b128 v[214:217], v155 offset:19456
	s_mov_b32 m0, s79
	s_nop 0
	global_load_lds_dwordx4 v132, s[76:77]
	ds_read_b128 v[226:229], v155 offset:20480
	ds_read_b128 v[234:237], v155 offset:21504
	s_add_i32 m0, s79, 0x2000
	s_nop 0
	global_load_lds_dwordx4 v136, s[76:77]
	ds_read_b128 v[238:241], v155 offset:22528
	ds_read_b128 v[242:245], v155 offset:23552
	s_mov_b32 m0, s53
	s_nop 0
	global_load_lds_dwordx4 v130, s[44:45]
	s_mov_b32 m0, s56
	s_nop 0
	global_load_lds_dwordx4 v134, s[44:45]
	s_waitcnt vmcnt(8)
	s_waitcnt lgkmcnt(0)
	s_barrier
	s_setprio 1
	s_waitcnt lgkmcnt(0)
	v_mfma_f32_16x16x32_bf16 v[62:65], v[158:161], v[190:193], v[62:65]
	v_mfma_f32_16x16x32_bf16 v[54:57], v[166:169], v[190:193], v[54:57]
	v_mfma_f32_16x16x32_bf16 v[46:49], v[158:161], v[210:213], v[46:49]
	v_mfma_f32_16x16x32_bf16 v[38:41], v[166:169], v[210:213], v[38:41]
	v_mfma_f32_16x16x32_bf16 v[30:33], v[158:161], v[226:229], v[30:33]
	v_mfma_f32_16x16x32_bf16 v[22:25], v[166:169], v[226:229], v[22:25]
	v_mfma_f32_16x16x32_bf16 v[14:17], v[158:161], v[238:241], v[14:17]
	v_mfma_f32_16x16x32_bf16 v[6:9], v[166:169], v[238:241], v[6:9]
	v_mfma_f32_16x16x32_bf16 v[62:65], v[162:165], v[206:209], v[62:65]
	v_mfma_f32_16x16x32_bf16 v[54:57], v[170:173], v[206:209], v[54:57]
	v_mfma_f32_16x16x32_bf16 v[46:49], v[162:165], v[214:217], v[46:49]
	v_mfma_f32_16x16x32_bf16 v[38:41], v[170:173], v[214:217], v[38:41]
	v_mfma_f32_16x16x32_bf16 v[30:33], v[162:165], v[234:237], v[30:33]
	v_mfma_f32_16x16x32_bf16 v[22:25], v[170:173], v[234:237], v[22:25]
	v_mfma_f32_16x16x32_bf16 v[14:17], v[162:165], v[242:245], v[14:17]
	v_mfma_f32_16x16x32_bf16 v[6:9], v[170:173], v[242:245], v[6:9]
	s_setprio 0
	s_setprio 1
	v_mfma_f32_16x16x32_bf16 v[58:61], v[174:177], v[190:193], v[58:61]
	v_mfma_f32_16x16x32_bf16 v[50:53], v[182:185], v[190:193], v[50:53]
	v_mfma_f32_16x16x32_bf16 v[42:45], v[174:177], v[210:213], v[42:45]
	v_mfma_f32_16x16x32_bf16 v[34:37], v[182:185], v[210:213], v[34:37]
	v_mfma_f32_16x16x32_bf16 v[26:29], v[174:177], v[226:229], v[26:29]
	v_mfma_f32_16x16x32_bf16 v[18:21], v[182:185], v[226:229], v[18:21]
	v_mfma_f32_16x16x32_bf16 v[10:13], v[174:177], v[238:241], v[10:13]
	v_mfma_f32_16x16x32_bf16 v[2:5], v[182:185], v[238:241], v[2:5]
	v_mfma_f32_16x16x32_bf16 v[58:61], v[178:181], v[206:209], v[58:61]
	v_mfma_f32_16x16x32_bf16 v[50:53], v[186:189], v[206:209], v[50:53]
	v_mfma_f32_16x16x32_bf16 v[42:45], v[178:181], v[214:217], v[42:45]
	v_mfma_f32_16x16x32_bf16 v[34:37], v[186:189], v[214:217], v[34:37]
	v_mfma_f32_16x16x32_bf16 v[26:29], v[178:181], v[234:237], v[26:29]
	v_mfma_f32_16x16x32_bf16 v[18:21], v[186:189], v[234:237], v[18:21]
	v_mfma_f32_16x16x32_bf16 v[10:13], v[178:181], v[242:245], v[10:13]
	v_mfma_f32_16x16x32_bf16 v[2:5], v[186:189], v[242:245], v[2:5]
	s_setprio 0
	s_barrier
; #define PG8_STAGE(bufoff, gbase, voff) do { _Pragma("unroll") for (int _i = 0; _i < 2; ++_i) \
;         __builtin_amdgcn_global_load_lds((const unsigned*)((const char*)(gbase) + (voff)[_i]), (PG8_LAS unsigned*)(lds + (bufoff) + ldsw + _i * 8192), 16, 0, 0); } while (0)
; #define PG8_LDA(dst, b, h) do { _Pragma("unroll") for (int m = 0; m < 4; ++m) _Pragma("unroll") for (int k = 0; k < 2; ++k) dst[m][k] = *(const PG8_LAS bf16x8*)(lds + PG8_SA(b, h) + aoff + m * 2048 + k * 1024); } while (0)
; #define PG8_LDB(dst, b, h) do { _Pragma("unroll") for (int n = 0; n < 2; ++n) _Pragma("unroll") for (int k = 0; k < 2; ++k) dst[n][k] = *(const PG8_LAS bf16x8*)(lds + PG8_SB(b, h) + boff + n * 2048 + k * 1024); } while (0)
; #define PG8_MMA(ai, bj, At, Bt) do { __builtin_amdgcn_s_setprio(1); _Pragma("unroll") for (int m = 0; m < 4; ++m) _Pragma("unroll") for (int n = 0; n < 2; ++n) _Pragma("unroll") for (int k = 0; k < 2; ++k) \
;         acc[ai][bj][m][n] = __builtin_amdgcn_mfma_f32_16x16x32_bf16(Bt[n][k], At[m][k], acc[ai][bj][m][n], 0, 0, 0); __builtin_amdgcn_s_setprio(0); } while (0)
; #define PG8_WAIT_V(n) asm volatile("s_waitcnt vmcnt(" #n ")" ::: "memory")
; #define PG8_WAIT_L(n) asm volatile("s_waitcnt lgkmcnt(" #n ")" ::: "memory")
; #define PG8_BAR __builtin_amdgcn_s_barrier()
; #define PG8_SCHED __builtin_amdgcn_sched_barrier(0)
; template <class Epi, class Sched, bool ALIGN_EPI = false, bool SP2 = false>
; __device__ __forceinline__ void gemm_phase(PG8_LAS unsigned char* lds, const Gemm g, const Sched& S, const Epi& E, const int wave_id) {
;     ...
;             PG8_LDB(B0, 1, 0); PG8_LDB(B1, 1, 1); PG8_SCHED; PG8_LDA(At, 1, 0); PG8_STAGE(PG8_SA(0, 1), a2 + hstep, voffA);
;             PG8_WAIT_V(8); PG8_WAIT_L(0); PG8_BAR; PG8_MMA(0, 0, At, B0); PG8_MMA(0, 1, At, B1); PG8_BAR; PG8_SCHED;
;             PG8_LDA(At, 1, 1); PG8_STAGE(PG8_SB(1, 0), b3, voffB); PG8_STAGE(PG8_SB(1, 1), b3 + hstep, voffB); PG8_STAGE(PG8_SA(1, 0), a3, voffA);
;             PG8_WAIT_V(8); PG8_WAIT_L(0); PG8_BAR; PG8_MMA(1, 0, At, B0); PG8_MMA(1, 1, At, B1); PG8_BAR; PG8_SCHED;
;     ...
;         if constexpr (ALIGN_EPI) { if (wr == 0) PG8_BAR; }
	s_add_i32 s76, 0, 0x18000
	s_add_i32 s77, 0, 0x1c000
	s_add_u32 s44, s44, 0x80000
	s_addc_u32 s45, s45, 0
	s_mov_b32 m0, s57
	s_nop 0
	global_load_lds_dwordx4 v130, s[44:45]
	ds_read_b128 v[158:161], v144 offset:32768
	ds_read_b128 v[162:165], v144 offset:33792
	ds_read_b128 v[166:169], v144 offset:34816
	ds_read_b128 v[170:173], v144 offset:35840
	ds_read_b128 v[174:177], v144 offset:49152
	ds_read_b128 v[178:181], v144 offset:50176
	ds_read_b128 v[182:185], v144 offset:51200
	ds_read_b128 v[186:189], v144 offset:52224
	s_mov_b32 m0, s64
	s_nop 0
	global_load_lds_dwordx4 v134, s[44:45]
	ds_read_b128 v[190:193], v155 offset:32768
	ds_read_b128 v[206:209], v155 offset:33792
	ds_read_b128 v[210:213], v155 offset:34816
	ds_read_b128 v[214:217], v155 offset:35840
	ds_read_b128 v[226:229], v155 offset:36864
	ds_read_b128 v[234:237], v155 offset:37888
	ds_read_b128 v[238:241], v155 offset:38912
	ds_read_b128 v[242:245], v155 offset:39936
	s_waitcnt vmcnt(8)
	s_waitcnt lgkmcnt(0)
	s_barrier
	s_setprio 1
	s_waitcnt lgkmcnt(0)
	v_mfma_f32_16x16x32_bf16 v[126:129], v[158:161], v[190:193], v[126:129]
	v_mfma_f32_16x16x32_bf16 v[118:121], v[166:169], v[190:193], v[118:121]
	v_mfma_f32_16x16x32_bf16 v[110:113], v[158:161], v[210:213], v[110:113]
	v_mfma_f32_16x16x32_bf16 v[102:105], v[166:169], v[210:213], v[102:105]
	v_mfma_f32_16x16x32_bf16 v[94:97], v[158:161], v[226:229], v[94:97]
	v_mfma_f32_16x16x32_bf16 v[86:89], v[166:169], v[226:229], v[86:89]
	v_mfma_f32_16x16x32_bf16 v[78:81], v[158:161], v[238:241], v[78:81]
	v_mfma_f32_16x16x32_bf16 v[70:73], v[166:169], v[238:241], v[70:73]
	v_mfma_f32_16x16x32_bf16 v[126:129], v[162:165], v[206:209], v[126:129]
	v_mfma_f32_16x16x32_bf16 v[118:121], v[170:173], v[206:209], v[118:121]
	v_mfma_f32_16x16x32_bf16 v[110:113], v[162:165], v[214:217], v[110:113]
	v_mfma_f32_16x16x32_bf16 v[102:105], v[170:173], v[214:217], v[102:105]
	v_mfma_f32_16x16x32_bf16 v[94:97], v[162:165], v[234:237], v[94:97]
	v_mfma_f32_16x16x32_bf16 v[86:89], v[170:173], v[234:237], v[86:89]
	v_mfma_f32_16x16x32_bf16 v[78:81], v[162:165], v[242:245], v[78:81]
	v_mfma_f32_16x16x32_bf16 v[70:73], v[170:173], v[242:245], v[70:73]
	s_setprio 0
	s_setprio 1
	v_mfma_f32_16x16x32_bf16 v[122:125], v[174:177], v[190:193], v[122:125]
	v_mfma_f32_16x16x32_bf16 v[114:117], v[182:185], v[190:193], v[114:117]
	v_mfma_f32_16x16x32_bf16 v[106:109], v[174:177], v[210:213], v[106:109]
	v_mfma_f32_16x16x32_bf16 v[98:101], v[182:185], v[210:213], v[98:101]
	v_mfma_f32_16x16x32_bf16 v[90:93], v[174:177], v[226:229], v[90:93]
	v_mfma_f32_16x16x32_bf16 v[82:85], v[182:185], v[226:229], v[82:85]
	v_mfma_f32_16x16x32_bf16 v[74:77], v[174:177], v[238:241], v[74:77]
	v_mfma_f32_16x16x32_bf16 v[66:69], v[182:185], v[238:241], v[66:69]
	v_mfma_f32_16x16x32_bf16 v[122:125], v[178:181], v[206:209], v[122:125]
	v_mfma_f32_16x16x32_bf16 v[114:117], v[186:189], v[206:209], v[114:117]
	v_mfma_f32_16x16x32_bf16 v[106:109], v[178:181], v[214:217], v[106:109]
	v_mfma_f32_16x16x32_bf16 v[98:101], v[186:189], v[214:217], v[98:101]
	v_mfma_f32_16x16x32_bf16 v[90:93], v[178:181], v[234:237], v[90:93]
	v_mfma_f32_16x16x32_bf16 v[82:85], v[186:189], v[234:237], v[82:85]
	v_mfma_f32_16x16x32_bf16 v[74:77], v[178:181], v[242:245], v[74:77]
	v_mfma_f32_16x16x32_bf16 v[66:69], v[186:189], v[242:245], v[66:69]
	s_setprio 0
	s_barrier
	s_add_u32 vcc_lo, s44, 0xfff80080
	s_addc_u32 vcc_hi, s45, -1
	s_mov_b32 m0, s65
	s_nop 0
	global_load_lds_dwordx4 v130, vcc
	ds_read_b128 v[190:193], v155 offset:49152
	ds_read_b128 v[206:209], v155 offset:50176
	s_mov_b32 m0, s68
	s_add_i32 s44, s76, s41
	global_load_lds_dwordx4 v134, vcc
	ds_read_b128 v[210:213], v155 offset:51200
	ds_read_b128 v[214:217], v155 offset:52224
	s_add_u32 vcc_lo, s42, 0x80
	s_addc_u32 vcc_hi, s43, 0
	s_mov_b32 m0, s44
	s_nop 0
	global_load_lds_dwordx4 v132, vcc
	ds_read_b128 v[226:229], v155 offset:53248
	ds_read_b128 v[234:237], v155 offset:54272
	s_add_i32 m0, s44, 0x2000
	s_add_u32 s42, s42, 0x80080
	s_addc_u32 s43, s43, 0
	global_load_lds_dwordx4 v136, vcc
	ds_read_b128 v[238:241], v155 offset:55296
	ds_read_b128 v[242:245], v155 offset:56320
	s_add_i32 s44, s77, s41
	s_mov_b32 m0, s44
	s_nop 0
	global_load_lds_dwordx4 v132, s[42:43]
	s_add_i32 m0, s44, 0x2000
	s_nop 0
	global_load_lds_dwordx4 v136, s[42:43]
	s_waitcnt vmcnt(8)
	s_waitcnt lgkmcnt(0)
	s_barrier
	s_setprio 1
	s_waitcnt lgkmcnt(0)
	v_mfma_f32_16x16x32_bf16 v[62:65], v[158:161], v[190:193], v[62:65]
	v_mfma_f32_16x16x32_bf16 v[54:57], v[166:169], v[190:193], v[54:57]
	v_mfma_f32_16x16x32_bf16 v[46:49], v[158:161], v[210:213], v[46:49]
	v_mfma_f32_16x16x32_bf16 v[38:41], v[166:169], v[210:213], v[38:41]
	v_mfma_f32_16x16x32_bf16 v[30:33], v[158:161], v[226:229], v[30:33]
	v_mfma_f32_16x16x32_bf16 v[22:25], v[166:169], v[226:229], v[22:25]
	v_mfma_f32_16x16x32_bf16 v[14:17], v[158:161], v[238:241], v[14:17]
	v_mfma_f32_16x16x32_bf16 v[6:9], v[166:169], v[238:241], v[6:9]
	v_mfma_f32_16x16x32_bf16 v[62:65], v[162:165], v[206:209], v[62:65]
	v_mfma_f32_16x16x32_bf16 v[54:57], v[170:173], v[206:209], v[54:57]
	v_mfma_f32_16x16x32_bf16 v[46:49], v[162:165], v[214:217], v[46:49]
	v_mfma_f32_16x16x32_bf16 v[38:41], v[170:173], v[214:217], v[38:41]
	v_mfma_f32_16x16x32_bf16 v[30:33], v[162:165], v[234:237], v[30:33]
	v_mfma_f32_16x16x32_bf16 v[22:25], v[170:173], v[234:237], v[22:25]
	v_mfma_f32_16x16x32_bf16 v[14:17], v[162:165], v[242:245], v[14:17]
	v_mfma_f32_16x16x32_bf16 v[6:9], v[170:173], v[242:245], v[6:9]
	s_setprio 0
	s_setprio 1
	v_mfma_f32_16x16x32_bf16 v[58:61], v[174:177], v[190:193], v[58:61]
	v_mfma_f32_16x16x32_bf16 v[50:53], v[182:185], v[190:193], v[50:53]
	v_mfma_f32_16x16x32_bf16 v[42:45], v[174:177], v[210:213], v[42:45]
	v_mfma_f32_16x16x32_bf16 v[34:37], v[182:185], v[210:213], v[34:37]
	v_mfma_f32_16x16x32_bf16 v[26:29], v[174:177], v[226:229], v[26:29]
	v_mfma_f32_16x16x32_bf16 v[18:21], v[182:185], v[226:229], v[18:21]
	v_mfma_f32_16x16x32_bf16 v[10:13], v[174:177], v[238:241], v[10:13]
	v_mfma_f32_16x16x32_bf16 v[2:5], v[182:185], v[238:241], v[2:5]
	v_mfma_f32_16x16x32_bf16 v[58:61], v[178:181], v[206:209], v[58:61]
	v_mfma_f32_16x16x32_bf16 v[50:53], v[186:189], v[206:209], v[50:53]
	v_mfma_f32_16x16x32_bf16 v[42:45], v[178:181], v[214:217], v[42:45]
	v_mfma_f32_16x16x32_bf16 v[34:37], v[186:189], v[214:217], v[34:37]
	v_mfma_f32_16x16x32_bf16 v[26:29], v[178:181], v[234:237], v[26:29]
	v_mfma_f32_16x16x32_bf16 v[18:21], v[186:189], v[234:237], v[18:21]
	v_mfma_f32_16x16x32_bf16 v[10:13], v[178:181], v[242:245], v[10:13]
	v_mfma_f32_16x16x32_bf16 v[2:5], v[186:189], v[242:245], v[2:5]
	s_setprio 0
	s_barrier
	s_add_i32 s75, s75, 2
	s_add_u32 s20, s20, 0x100
	s_addc_u32 s21, s21, 0
	s_add_u32 s73, s73, 0x100
	s_addc_u32 s74, s74, 0
	s_cmp_gt_u32 s75, 29
	s_cbranch_scc0 .LBB0_641
	s_and_b64 vcc, exec, s[10:11]
	s_cbranch_vccz .LBB0_644
	s_barrier

; #define PG8_STAGE(bufoff, gbase, voff) do { _Pragma("unroll") for (int _i = 0; _i < 2; ++_i) \
;         __builtin_amdgcn_global_load_lds((const unsigned*)((const char*)(gbase) + (voff)[_i]), (PG8_LAS unsigned*)(lds + (bufoff) + ldsw + _i * 8192), 16, 0, 0); } while (0)
; #define PG8_LDA(dst, b, h) do { _Pragma("unroll") for (int m = 0; m < 4; ++m) _Pragma("unroll") for (int k = 0; k < 2; ++k) dst[m][k] = *(const PG8_LAS bf16x8*)(lds + PG8_SA(b, h) + aoff + m * 2048 + k * 1024); } while (0)
; #define PG8_LDB(dst, b, h) do { _Pragma("unroll") for (int n = 0; n < 2; ++n) _Pragma("unroll") for (int k = 0; k < 2; ++k) dst[n][k] = *(const PG8_LAS bf16x8*)(lds + PG8_SB(b, h) + boff + n * 2048 + k * 1024); } while (0)
; #define PG8_MMA(ai, bj, At, Bt) do { __builtin_amdgcn_s_setprio(1); _Pragma("unroll") for (int m = 0; m < 4; ++m) _Pragma("unroll") for (int n = 0; n < 2; ++n) _Pragma("unroll") for (int k = 0; k < 2; ++k) \
;         acc[ai][bj][m][n] = __builtin_amdgcn_mfma_f32_16x16x32_bf16(Bt[n][k], At[m][k], acc[ai][bj][m][n], 0, 0, 0); __builtin_amdgcn_s_setprio(0); } while (0)
; #define PG8_WAIT_V(n) asm volatile("s_waitcnt vmcnt(" #n ")" ::: "memory")
; #define PG8_BAR __builtin_amdgcn_s_barrier()
; template <class Epi, class Sched, bool ALIGN_EPI = false, bool SP2 = false>
; __device__ __forceinline__ void gemm_phase(PG8_LAS unsigned char* lds, const Gemm g, const Sched& S, const Epi& E, const int wave_id) {
;     ...
;         for (int t = 0; t < nt; t += 2) {
;             const bool last = (t == nt - 2);
;             const char* a1 = cA + (size_t)(t + 1) * kstep;
;             const char* a2 = last ? nA : cA + (size_t)(t + 2) * kstep; const char* b2 = last ? nB : cB + (size_t)(t + 2) * kstep;
;             const char* a3 = a2 + kstep; const char* b3 = b2 + kstep;
;             if (last && has_next) S.a_ready(nxt);
;             if constexpr (SP2) {
;             PG8_LDB(B0, 0, 0); PG8_LDB(B1, 0, 1); PG8_SCHED; PG8_LDA(At, 0, 0); PG8_STAGE(PG8_SA(1, 1), a1 + hstep, voffA);
;             PG8_WAIT_V(8); PG8_WAIT_L(0); PG8_BAR; PG8_MMA(0, 0, At, B0); PG8_MMA(0, 1, At, B1); PG8_BAR; PG8_SCHED;
;             PG8_LDA(At, 0, 1); PG8_STAGE(PG8_SB(0, 0), b2, voffB); PG8_STAGE(PG8_SB(0, 1), b2 + hstep, voffB); PG8_STAGE(PG8_SA(0, 0), a2, voffA);
;             PG8_WAIT_V(8); PG8_WAIT_L(0); PG8_BAR; PG8_MMA(1, 0, At, B0); PG8_MMA(1, 1, At, B1); PG8_BAR; PG8_SCHED;
.LBB0_759:
	s_add_u32 s20, s18, 0x100
	s_addc_u32 s21, s19, 0
	s_add_i32 s77, 0, 0x10000
	s_cmpk_eq_i32 s76, 0x54
	s_cselect_b32 s43, s15, s21
	s_cselect_b32 s42, s14, s20
	s_cselect_b32 s41, s17, s75
	s_cselect_b32 s40, s16, s74
	s_add_i32 s79, 0, 0x14000
	s_add_i32 m0, s52, 0xc000
	s_nop 0
	global_load_lds_dwordx4 v210, s[18:19]
	ds_read_b128 v[118:121], v226
	ds_read_b128 v[122:125], v226 offset:1024
	ds_read_b128 v[130:133], v226 offset:2048
	ds_read_b128 v[134:137], v226 offset:3072
	ds_read_b128 v[146:149], v226 offset:16384
	ds_read_b128 v[150:153], v226 offset:17408
	ds_read_b128 v[154:157], v226 offset:18432
	ds_read_b128 v[158:161], v226 offset:19456
	s_add_i32 m0, s52, 0xe000
	s_nop 0
	global_load_lds_dwordx4 v212, s[18:19]
	ds_read_b128 v[162:165], v222
	ds_read_b128 v[166:169], v222 offset:1024
	ds_read_b128 v[170:173], v222 offset:2048
	ds_read_b128 v[174:177], v222 offset:3072
	ds_read_b128 v[178:181], v222 offset:4096
	ds_read_b128 v[182:185], v222 offset:5120
	ds_read_b128 v[186:189], v222 offset:6144
	ds_read_b128 v[214:217], v222 offset:7168
	s_waitcnt vmcnt(8)
	s_waitcnt lgkmcnt(0)
	s_barrier
	s_setprio 1
	s_waitcnt lgkmcnt(0)
	v_mfma_f32_16x16x32_bf16 v[142:145], v[118:121], v[162:165], v[142:145]
	v_mfma_f32_16x16x32_bf16 v[138:141], v[130:133], v[162:165], v[138:141]
	v_mfma_f32_16x16x32_bf16 v[110:113], v[118:121], v[170:173], v[110:113]
	v_mfma_f32_16x16x32_bf16 v[106:109], v[130:133], v[170:173], v[106:109]
	v_mfma_f32_16x16x32_bf16 v[94:97], v[118:121], v[178:181], v[94:97]
	v_mfma_f32_16x16x32_bf16 v[90:93], v[130:133], v[178:181], v[90:93]
	v_mfma_f32_16x16x32_bf16 v[78:81], v[118:121], v[186:189], v[78:81]
	v_mfma_f32_16x16x32_bf16 v[74:77], v[130:133], v[186:189], v[74:77]
	v_mfma_f32_16x16x32_bf16 v[142:145], v[122:125], v[166:169], v[142:145]
	v_mfma_f32_16x16x32_bf16 v[138:141], v[134:137], v[166:169], v[138:141]
	v_mfma_f32_16x16x32_bf16 v[110:113], v[122:125], v[174:177], v[110:113]
	v_mfma_f32_16x16x32_bf16 v[106:109], v[134:137], v[174:177], v[106:109]
	v_mfma_f32_16x16x32_bf16 v[94:97], v[122:125], v[182:185], v[94:97]
	v_mfma_f32_16x16x32_bf16 v[90:93], v[134:137], v[182:185], v[90:93]
	v_mfma_f32_16x16x32_bf16 v[78:81], v[122:125], v[214:217], v[78:81]
	v_mfma_f32_16x16x32_bf16 v[74:77], v[134:137], v[214:217], v[74:77]
	s_setprio 0
	s_setprio 1
	v_mfma_f32_16x16x32_bf16 v[126:129], v[146:149], v[162:165], v[126:129]
	v_mfma_f32_16x16x32_bf16 v[114:117], v[154:157], v[162:165], v[114:117]
	v_mfma_f32_16x16x32_bf16 v[102:105], v[146:149], v[170:173], v[102:105]
	v_mfma_f32_16x16x32_bf16 v[98:101], v[154:157], v[170:173], v[98:101]
	v_mfma_f32_16x16x32_bf16 v[86:89], v[146:149], v[178:181], v[86:89]
	v_mfma_f32_16x16x32_bf16 v[82:85], v[154:157], v[178:181], v[82:85]
	v_mfma_f32_16x16x32_bf16 v[70:73], v[146:149], v[186:189], v[70:73]
	v_mfma_f32_16x16x32_bf16 v[66:69], v[154:157], v[186:189], v[66:69]
	v_mfma_f32_16x16x32_bf16 v[126:129], v[150:153], v[166:169], v[126:129]
	v_mfma_f32_16x16x32_bf16 v[114:117], v[158:161], v[166:169], v[114:117]
	v_mfma_f32_16x16x32_bf16 v[102:105], v[150:153], v[174:177], v[102:105]
	v_mfma_f32_16x16x32_bf16 v[98:101], v[158:161], v[174:177], v[98:101]
	v_mfma_f32_16x16x32_bf16 v[86:89], v[150:153], v[182:185], v[86:89]
	v_mfma_f32_16x16x32_bf16 v[82:85], v[158:161], v[182:185], v[82:85]
	v_mfma_f32_16x16x32_bf16 v[70:73], v[150:153], v[214:217], v[70:73]
	v_mfma_f32_16x16x32_bf16 v[66:69], v[158:161], v[214:217], v[66:69]
	s_setprio 0
	s_barrier
	s_add_i32 s18, s77, s49
	s_mov_b32 m0, s18
	s_nop 0
	global_load_lds_dwordx4 v192, s[40:41]
	ds_read_b128 v[162:165], v222 offset:16384
	ds_read_b128 v[166:169], v222 offset:17408
	s_add_i32 m0, s18, 0x2000
	s_add_u32 s18, s40, 0x160000
	s_addc_u32 s19, s41, 0
	s_add_i32 s77, s79, s49
	global_load_lds_dwordx4 v208, s[40:41]
	ds_read_b128 v[170:173], v222 offset:18432
	ds_read_b128 v[174:177], v222 offset:19456
	s_mov_b32 m0, s77
	s_nop 0
	global_load_lds_dwordx4 v192, s[18:19]
	ds_read_b128 v[178:181], v222 offset:20480
	ds_read_b128 v[182:185], v222 offset:21504
	s_add_i32 m0, s77, 0x2000
	s_nop 0
	global_load_lds_dwordx4 v208, s[18:19]
	ds_read_b128 v[186:189], v222 offset:22528
	ds_read_b128 v[214:217], v222 offset:23552
	s_mov_b32 m0, s52
	s_nop 0
	global_load_lds_dwordx4 v190, s[42:43]
	s_mov_b32 m0, s53
	s_nop 0
	global_load_lds_dwordx4 v206, s[42:43]
	s_waitcnt vmcnt(8)
	s_waitcnt lgkmcnt(0)
	s_barrier
	s_setprio 1
	s_waitcnt lgkmcnt(0)
	v_mfma_f32_16x16x32_bf16 v[62:65], v[118:121], v[162:165], v[62:65]
	v_mfma_f32_16x16x32_bf16 v[58:61], v[130:133], v[162:165], v[58:61]
	v_mfma_f32_16x16x32_bf16 v[46:49], v[118:121], v[170:173], v[46:49]
	v_mfma_f32_16x16x32_bf16 v[42:45], v[130:133], v[170:173], v[42:45]
	v_mfma_f32_16x16x32_bf16 v[30:33], v[118:121], v[178:181], v[30:33]
	v_mfma_f32_16x16x32_bf16 v[26:29], v[130:133], v[178:181], v[26:29]
	v_mfma_f32_16x16x32_bf16 v[14:17], v[118:121], v[186:189], v[14:17]
	v_mfma_f32_16x16x32_bf16 v[10:13], v[130:133], v[186:189], v[10:13]
	v_mfma_f32_16x16x32_bf16 v[62:65], v[122:125], v[166:169], v[62:65]
	v_mfma_f32_16x16x32_bf16 v[58:61], v[134:137], v[166:169], v[58:61]
	v_mfma_f32_16x16x32_bf16 v[46:49], v[122:125], v[174:177], v[46:49]
	v_mfma_f32_16x16x32_bf16 v[42:45], v[134:137], v[174:177], v[42:45]
	v_mfma_f32_16x16x32_bf16 v[30:33], v[122:125], v[182:185], v[30:33]
	v_mfma_f32_16x16x32_bf16 v[26:29], v[134:137], v[182:185], v[26:29]
	v_mfma_f32_16x16x32_bf16 v[14:17], v[122:125], v[214:217], v[14:17]
	v_mfma_f32_16x16x32_bf16 v[10:13], v[134:137], v[214:217], v[10:13]
	s_setprio 0
	s_setprio 1
	v_mfma_f32_16x16x32_bf16 v[54:57], v[146:149], v[162:165], v[54:57]
	v_mfma_f32_16x16x32_bf16 v[50:53], v[154:157], v[162:165], v[50:53]
	v_mfma_f32_16x16x32_bf16 v[38:41], v[146:149], v[170:173], v[38:41]
	v_mfma_f32_16x16x32_bf16 v[34:37], v[154:157], v[170:173], v[34:37]
	v_mfma_f32_16x16x32_bf16 v[22:25], v[146:149], v[178:181], v[22:25]
	v_mfma_f32_16x16x32_bf16 v[18:21], v[154:157], v[178:181], v[18:21]
	v_mfma_f32_16x16x32_bf16 v[6:9], v[146:149], v[186:189], v[6:9]
	v_mfma_f32_16x16x32_bf16 v[2:5], v[154:157], v[186:189], v[2:5]
	v_mfma_f32_16x16x32_bf16 v[54:57], v[150:153], v[166:169], v[54:57]
	v_mfma_f32_16x16x32_bf16 v[50:53], v[158:161], v[166:169], v[50:53]
	v_mfma_f32_16x16x32_bf16 v[38:41], v[150:153], v[174:177], v[38:41]
	v_mfma_f32_16x16x32_bf16 v[34:37], v[158:161], v[174:177], v[34:37]
	v_mfma_f32_16x16x32_bf16 v[22:25], v[150:153], v[182:185], v[22:25]
	v_mfma_f32_16x16x32_bf16 v[18:21], v[158:161], v[182:185], v[18:21]
	v_mfma_f32_16x16x32_bf16 v[6:9], v[150:153], v[214:217], v[6:9]
	v_mfma_f32_16x16x32_bf16 v[2:5], v[158:161], v[214:217], v[2:5]
	s_setprio 0
	s_barrier
; #define PG8_STAGE(bufoff, gbase, voff) do { _Pragma("unroll") for (int _i = 0; _i < 2; ++_i) \
;         __builtin_amdgcn_global_load_lds((const unsigned*)((const char*)(gbase) + (voff)[_i]), (PG8_LAS unsigned*)(lds + (bufoff) + ldsw + _i * 8192), 16, 0, 0); } while (0)
; #define PG8_LDA(dst, b, h) do { _Pragma("unroll") for (int m = 0; m < 4; ++m) _Pragma("unroll") for (int k = 0; k < 2; ++k) dst[m][k] = *(const PG8_LAS bf16x8*)(lds + PG8_SA(b, h) + aoff + m * 2048 + k * 1024); } while (0)
; #define PG8_LDB(dst, b, h) do { _Pragma("unroll") for (int n = 0; n < 2; ++n) _Pragma("unroll") for (int k = 0; k < 2; ++k) dst[n][k] = *(const PG8_LAS bf16x8*)(lds + PG8_SB(b, h) + boff + n * 2048 + k * 1024); } while (0)
; #define PG8_MMA(ai, bj, At, Bt) do { __builtin_amdgcn_s_setprio(1); _Pragma("unroll") for (int m = 0; m < 4; ++m) _Pragma("unroll") for (int n = 0; n < 2; ++n) _Pragma("unroll") for (int k = 0; k < 2; ++k) \
;         acc[ai][bj][m][n] = __builtin_amdgcn_mfma_f32_16x16x32_bf16(Bt[n][k], At[m][k], acc[ai][bj][m][n], 0, 0, 0); __builtin_amdgcn_s_setprio(0); } while (0)
; #define PG8_WAIT_V(n) asm volatile("s_waitcnt vmcnt(" #n ")" ::: "memory")
; #define PG8_WAIT_L(n) asm volatile("s_waitcnt lgkmcnt(" #n ")" ::: "memory")
; #define PG8_BAR __builtin_amdgcn_s_barrier()
; #define PG8_SCHED __builtin_amdgcn_sched_barrier(0)
; template <class Epi, class Sched, bool ALIGN_EPI = false, bool SP2 = false>
; __device__ __forceinline__ void gemm_phase(PG8_LAS unsigned char* lds, const Gemm g, const Sched& S, const Epi& E, const int wave_id) {
;     ...
;             PG8_LDB(B0, 1, 0); PG8_LDB(B1, 1, 1); PG8_SCHED; PG8_LDA(At, 1, 0); PG8_STAGE(PG8_SA(0, 1), a2 + hstep, voffA);
;             PG8_WAIT_V(8); PG8_WAIT_L(0); PG8_BAR; PG8_MMA(0, 0, At, B0); PG8_MMA(0, 1, At, B1); PG8_BAR; PG8_SCHED;
;             PG8_LDA(At, 1, 1); PG8_STAGE(PG8_SB(1, 0), b3, voffB); PG8_STAGE(PG8_SB(1, 1), b3 + hstep, voffB); PG8_STAGE(PG8_SA(1, 0), a3, voffA);
;             PG8_WAIT_V(8); PG8_WAIT_L(0); PG8_BAR; PG8_MMA(1, 0, At, B0); PG8_MMA(1, 1, At, B1); PG8_BAR; PG8_SCHED;
;     ...
;         if constexpr (ALIGN_EPI) { if (wr == 0) PG8_BAR; }
	s_add_i32 s77, 0, 0x18000
	s_add_i32 s79, 0, 0x1c000
	s_add_u32 s18, s42, 0x160000
	s_addc_u32 s19, s43, 0
	s_mov_b32 m0, s56
	s_nop 0
	global_load_lds_dwordx4 v190, s[18:19]
	ds_read_b128 v[118:121], v226 offset:32768
	ds_read_b128 v[122:125], v226 offset:33792
	ds_read_b128 v[130:133], v226 offset:34816
	ds_read_b128 v[134:137], v226 offset:35840
	ds_read_b128 v[146:149], v226 offset:49152
	ds_read_b128 v[150:153], v226 offset:50176
	ds_read_b128 v[154:157], v226 offset:51200
	ds_read_b128 v[158:161], v226 offset:52224
	s_mov_b32 m0, s57
	s_nop 0
	global_load_lds_dwordx4 v206, s[18:19]
	ds_read_b128 v[162:165], v222 offset:32768
	ds_read_b128 v[166:169], v222 offset:33792
	ds_read_b128 v[170:173], v222 offset:34816
	ds_read_b128 v[174:177], v222 offset:35840
	ds_read_b128 v[178:181], v222 offset:36864
	ds_read_b128 v[182:185], v222 offset:37888
	ds_read_b128 v[186:189], v222 offset:38912
	ds_read_b128 v[214:217], v222 offset:39936
	s_waitcnt vmcnt(8)
	s_waitcnt lgkmcnt(0)
	s_barrier
	s_setprio 1
	s_waitcnt lgkmcnt(0)
	v_mfma_f32_16x16x32_bf16 v[142:145], v[118:121], v[162:165], v[142:145]
	v_mfma_f32_16x16x32_bf16 v[138:141], v[130:133], v[162:165], v[138:141]
	v_mfma_f32_16x16x32_bf16 v[110:113], v[118:121], v[170:173], v[110:113]
	v_mfma_f32_16x16x32_bf16 v[106:109], v[130:133], v[170:173], v[106:109]
	v_mfma_f32_16x16x32_bf16 v[94:97], v[118:121], v[178:181], v[94:97]
	v_mfma_f32_16x16x32_bf16 v[90:93], v[130:133], v[178:181], v[90:93]
	v_mfma_f32_16x16x32_bf16 v[78:81], v[118:121], v[186:189], v[78:81]
	v_mfma_f32_16x16x32_bf16 v[74:77], v[130:133], v[186:189], v[74:77]
	v_mfma_f32_16x16x32_bf16 v[142:145], v[122:125], v[166:169], v[142:145]
	v_mfma_f32_16x16x32_bf16 v[138:141], v[134:137], v[166:169], v[138:141]
	v_mfma_f32_16x16x32_bf16 v[110:113], v[122:125], v[174:177], v[110:113]
	v_mfma_f32_16x16x32_bf16 v[106:109], v[134:137], v[174:177], v[106:109]
	v_mfma_f32_16x16x32_bf16 v[94:97], v[122:125], v[182:185], v[94:97]
	v_mfma_f32_16x16x32_bf16 v[90:93], v[134:137], v[182:185], v[90:93]
	v_mfma_f32_16x16x32_bf16 v[78:81], v[122:125], v[214:217], v[78:81]
	v_mfma_f32_16x16x32_bf16 v[74:77], v[134:137], v[214:217], v[74:77]
	s_setprio 0
	s_setprio 1
	v_mfma_f32_16x16x32_bf16 v[126:129], v[146:149], v[162:165], v[126:129]
	v_mfma_f32_16x16x32_bf16 v[114:117], v[154:157], v[162:165], v[114:117]
	v_mfma_f32_16x16x32_bf16 v[102:105], v[146:149], v[170:173], v[102:105]
	v_mfma_f32_16x16x32_bf16 v[98:101], v[154:157], v[170:173], v[98:101]
	v_mfma_f32_16x16x32_bf16 v[86:89], v[146:149], v[178:181], v[86:89]
	v_mfma_f32_16x16x32_bf16 v[82:85], v[154:157], v[178:181], v[82:85]
	v_mfma_f32_16x16x32_bf16 v[70:73], v[146:149], v[186:189], v[70:73]
	v_mfma_f32_16x16x32_bf16 v[66:69], v[154:157], v[186:189], v[66:69]
	v_mfma_f32_16x16x32_bf16 v[126:129], v[150:153], v[166:169], v[126:129]
	v_mfma_f32_16x16x32_bf16 v[114:117], v[158:161], v[166:169], v[114:117]
	v_mfma_f32_16x16x32_bf16 v[102:105], v[150:153], v[174:177], v[102:105]
	v_mfma_f32_16x16x32_bf16 v[98:101], v[158:161], v[174:177], v[98:101]
	v_mfma_f32_16x16x32_bf16 v[86:89], v[150:153], v[182:185], v[86:89]
	v_mfma_f32_16x16x32_bf16 v[82:85], v[158:161], v[182:185], v[82:85]
	v_mfma_f32_16x16x32_bf16 v[70:73], v[150:153], v[214:217], v[70:73]
	v_mfma_f32_16x16x32_bf16 v[66:69], v[158:161], v[214:217], v[66:69]
	s_setprio 0
	s_barrier
	s_add_u32 vcc_lo, s42, 0x80
	s_addc_u32 vcc_hi, s43, 0
	s_mov_b32 m0, s68
	s_nop 0
	global_load_lds_dwordx4 v190, vcc
	ds_read_b128 v[162:165], v222 offset:49152
	ds_read_b128 v[166:169], v222 offset:50176
	s_mov_b32 m0, s69
	s_add_i32 s18, s77, s49
	global_load_lds_dwordx4 v206, vcc
	ds_read_b128 v[170:173], v222 offset:51200
	ds_read_b128 v[174:177], v222 offset:52224
	s_add_u32 vcc_lo, s40, 0x80
	s_addc_u32 vcc_hi, s41, 0
	s_mov_b32 m0, s18
	s_nop 0
	global_load_lds_dwordx4 v192, vcc
	ds_read_b128 v[178:181], v222 offset:53248
	ds_read_b128 v[182:185], v222 offset:54272
	s_add_i32 m0, s18, 0x2000
	s_add_u32 s18, s40, 0x160080
	s_addc_u32 s19, s41, 0
	global_load_lds_dwordx4 v208, vcc
	ds_read_b128 v[186:189], v222 offset:55296
	ds_read_b128 v[214:217], v222 offset:56320
	s_add_i32 s40, s79, s49
	s_mov_b32 m0, s40
	s_nop 0
	global_load_lds_dwordx4 v192, s[18:19]
	s_add_i32 m0, s40, 0x2000
	s_nop 0
	global_load_lds_dwordx4 v208, s[18:19]
	s_waitcnt vmcnt(8)
	s_waitcnt lgkmcnt(0)
	s_barrier
	s_setprio 1
	s_waitcnt lgkmcnt(0)
	v_mfma_f32_16x16x32_bf16 v[62:65], v[118:121], v[162:165], v[62:65]
	v_mfma_f32_16x16x32_bf16 v[58:61], v[130:133], v[162:165], v[58:61]
	v_mfma_f32_16x16x32_bf16 v[46:49], v[118:121], v[170:173], v[46:49]
	v_mfma_f32_16x16x32_bf16 v[42:45], v[130:133], v[170:173], v[42:45]
	v_mfma_f32_16x16x32_bf16 v[30:33], v[118:121], v[178:181], v[30:33]
	v_mfma_f32_16x16x32_bf16 v[26:29], v[130:133], v[178:181], v[26:29]
	v_mfma_f32_16x16x32_bf16 v[14:17], v[118:121], v[186:189], v[14:17]
	v_mfma_f32_16x16x32_bf16 v[10:13], v[130:133], v[186:189], v[10:13]
	v_mfma_f32_16x16x32_bf16 v[62:65], v[122:125], v[166:169], v[62:65]
	v_mfma_f32_16x16x32_bf16 v[58:61], v[134:137], v[166:169], v[58:61]
	v_mfma_f32_16x16x32_bf16 v[46:49], v[122:125], v[174:177], v[46:49]
	v_mfma_f32_16x16x32_bf16 v[42:45], v[134:137], v[174:177], v[42:45]
	v_mfma_f32_16x16x32_bf16 v[30:33], v[122:125], v[182:185], v[30:33]
	v_mfma_f32_16x16x32_bf16 v[26:29], v[134:137], v[182:185], v[26:29]
	v_mfma_f32_16x16x32_bf16 v[14:17], v[122:125], v[214:217], v[14:17]
	v_mfma_f32_16x16x32_bf16 v[10:13], v[134:137], v[214:217], v[10:13]
	s_setprio 0
	s_setprio 1
	v_mfma_f32_16x16x32_bf16 v[54:57], v[146:149], v[162:165], v[54:57]
	v_mfma_f32_16x16x32_bf16 v[50:53], v[154:157], v[162:165], v[50:53]
	v_mfma_f32_16x16x32_bf16 v[38:41], v[146:149], v[170:173], v[38:41]
	v_mfma_f32_16x16x32_bf16 v[34:37], v[154:157], v[170:173], v[34:37]
	v_mfma_f32_16x16x32_bf16 v[22:25], v[146:149], v[178:181], v[22:25]
	v_mfma_f32_16x16x32_bf16 v[18:21], v[154:157], v[178:181], v[18:21]
	v_mfma_f32_16x16x32_bf16 v[6:9], v[146:149], v[186:189], v[6:9]
	v_mfma_f32_16x16x32_bf16 v[2:5], v[154:157], v[186:189], v[2:5]
	v_mfma_f32_16x16x32_bf16 v[54:57], v[150:153], v[166:169], v[54:57]
	v_mfma_f32_16x16x32_bf16 v[50:53], v[158:161], v[166:169], v[50:53]
	v_mfma_f32_16x16x32_bf16 v[38:41], v[150:153], v[174:177], v[38:41]
	v_mfma_f32_16x16x32_bf16 v[34:37], v[158:161], v[174:177], v[34:37]
	v_mfma_f32_16x16x32_bf16 v[22:25], v[150:153], v[182:185], v[22:25]
	v_mfma_f32_16x16x32_bf16 v[18:21], v[158:161], v[182:185], v[18:21]
	v_mfma_f32_16x16x32_bf16 v[6:9], v[150:153], v[214:217], v[6:9]
	v_mfma_f32_16x16x32_bf16 v[2:5], v[158:161], v[214:217], v[2:5]
	s_setprio 0
	s_barrier
	s_add_i32 s76, s76, 2
	s_add_u32 s74, s74, 0x100
	s_addc_u32 s75, s75, 0
	s_cmpk_gt_u32 s76, 0x55
	s_mov_b64 s[18:19], s[20:21]
	s_cbranch_scc0 .LBB0_759
	s_and_b64 vcc, exec, s[10:11]
	s_cbranch_vccz .LBB0_762
	s_barrier

; #define PG8_STAGE(bufoff, gbase, voff) do { _Pragma("unroll") for (int _i = 0; _i < 2; ++_i) \
;         __builtin_amdgcn_global_load_lds((const unsigned*)((const char*)(gbase) + (voff)[_i]), (PG8_LAS unsigned*)(lds + (bufoff) + ldsw + _i * 8192), 16, 0, 0); } while (0)
; #define PG8_LDA(dst, b, h) do { _Pragma("unroll") for (int m = 0; m < 4; ++m) _Pragma("unroll") for (int k = 0; k < 2; ++k) dst[m][k] = *(const PG8_LAS bf16x8*)(lds + PG8_SA(b, h) + aoff + m * 2048 + k * 1024); } while (0)
; #define PG8_LDB(dst, b, h) do { _Pragma("unroll") for (int n = 0; n < 2; ++n) _Pragma("unroll") for (int k = 0; k < 2; ++k) dst[n][k] = *(const PG8_LAS bf16x8*)(lds + PG8_SB(b, h) + boff + n * 2048 + k * 1024); } while (0)
; #define PG8_MMA(ai, bj, At, Bt) do { __builtin_amdgcn_s_setprio(1); _Pragma("unroll") for (int m = 0; m < 4; ++m) _Pragma("unroll") for (int n = 0; n < 2; ++n) _Pragma("unroll") for (int k = 0; k < 2; ++k) \
;         acc[ai][bj][m][n] = __builtin_amdgcn_mfma_f32_16x16x32_bf16(Bt[n][k], At[m][k], acc[ai][bj][m][n], 0, 0, 0); __builtin_amdgcn_s_setprio(0); } while (0)
; #define PG8_WAIT_V(n) asm volatile("s_waitcnt vmcnt(" #n ")" ::: "memory")
; #define PG8_BAR __builtin_amdgcn_s_barrier()
; template <class Epi, class Sched, bool ALIGN_EPI = false, bool SP2 = false>
; __device__ __forceinline__ void gemm_phase(PG8_LAS unsigned char* lds, const Gemm g, const Sched& S, const Epi& E, const int wave_id) {
;     ...
;         for (int t = 0; t < nt; t += 2) {
;             const bool last = (t == nt - 2);
;             const char* a1 = cA + (size_t)(t + 1) * kstep;
;             const char* a2 = last ? nA : cA + (size_t)(t + 2) * kstep; const char* b2 = last ? nB : cB + (size_t)(t + 2) * kstep;
;             const char* a3 = a2 + kstep; const char* b3 = b2 + kstep;
;             if (last && has_next) S.a_ready(nxt);
;             if constexpr (SP2) {
;             PG8_LDB(B0, 0, 0); PG8_LDB(B1, 0, 1); PG8_SCHED; PG8_LDA(At, 0, 0); PG8_STAGE(PG8_SA(1, 1), a1 + hstep, voffA);
;             PG8_WAIT_V(8); PG8_WAIT_L(0); PG8_BAR; PG8_MMA(0, 0, At, B0); PG8_MMA(0, 1, At, B1); PG8_BAR; PG8_SCHED;
;             PG8_LDA(At, 0, 1); PG8_STAGE(PG8_SB(0, 0), b2, voffB); PG8_STAGE(PG8_SB(0, 1), b2 + hstep, voffB); PG8_STAGE(PG8_SA(0, 0), a2, voffA);
;             PG8_WAIT_V(8); PG8_WAIT_L(0); PG8_BAR; PG8_MMA(1, 0, At, B0); PG8_MMA(1, 1, At, B1); PG8_BAR; PG8_SCHED;
.LBB0_904:
	s_add_u32 s52, s46, 0xfff80080
	s_addc_u32 s53, s47, -1
	s_add_i32 s85, 0, 0x10000
	s_cmp_eq_u32 s84, 28
	s_cselect_b32 s83, s21, s53
	s_cselect_b32 s82, s49, s52
	s_cselect_b32 s53, s19, s81
	s_cselect_b32 s52, s79, s80
	s_add_i32 s92, 0, 0x14000
	s_add_i32 m0, s70, 0xc000
	s_nop 0
	global_load_lds_dwordx4 v214, s[46:47]
	ds_read_b128 v[114:117], v226
	ds_read_b128 v[118:121], v226 offset:1024
	ds_read_b128 v[130:133], v226 offset:2048
	ds_read_b128 v[134:137], v226 offset:3072
	ds_read_b128 v[138:141], v226 offset:16384
	ds_read_b128 v[142:145], v226 offset:17408
	ds_read_b128 v[146:149], v226 offset:18432
	ds_read_b128 v[150:153], v226 offset:19456
	s_add_i32 m0, s70, 0xe000
	s_nop 0
	global_load_lds_dwordx4 v216, s[46:47]
	ds_read_b128 v[162:165], v244
	ds_read_b128 v[166:169], v244 offset:1024
	ds_read_b128 v[170:173], v244 offset:2048
	ds_read_b128 v[174:177], v244 offset:3072
	ds_read_b128 v[178:181], v244 offset:4096
	ds_read_b128 v[182:185], v244 offset:5120
	ds_read_b128 v[186:189], v244 offset:6144
	ds_read_b128 v[190:193], v244 offset:7168
	s_waitcnt vmcnt(8)
	s_waitcnt lgkmcnt(0)
	s_barrier
	s_setprio 1
	s_waitcnt lgkmcnt(0)
	v_mfma_f32_16x16x32_bf16 v[158:161], v[114:117], v[162:165], v[158:161]
	v_mfma_f32_16x16x32_bf16 v[154:157], v[130:133], v[162:165], v[154:157]
	v_mfma_f32_16x16x32_bf16 v[110:113], v[114:117], v[170:173], v[110:113]
	v_mfma_f32_16x16x32_bf16 v[106:109], v[130:133], v[170:173], v[106:109]
	v_mfma_f32_16x16x32_bf16 v[94:97], v[114:117], v[178:181], v[94:97]
	v_mfma_f32_16x16x32_bf16 v[90:93], v[130:133], v[178:181], v[90:93]
	v_mfma_f32_16x16x32_bf16 v[78:81], v[114:117], v[186:189], v[78:81]
	v_mfma_f32_16x16x32_bf16 v[74:77], v[130:133], v[186:189], v[74:77]
	v_mfma_f32_16x16x32_bf16 v[158:161], v[118:121], v[166:169], v[158:161]
	v_mfma_f32_16x16x32_bf16 v[154:157], v[134:137], v[166:169], v[154:157]
	v_mfma_f32_16x16x32_bf16 v[110:113], v[118:121], v[174:177], v[110:113]
	v_mfma_f32_16x16x32_bf16 v[106:109], v[134:137], v[174:177], v[106:109]
	v_mfma_f32_16x16x32_bf16 v[94:97], v[118:121], v[182:185], v[94:97]
	v_mfma_f32_16x16x32_bf16 v[90:93], v[134:137], v[182:185], v[90:93]
	v_mfma_f32_16x16x32_bf16 v[78:81], v[118:121], v[190:193], v[78:81]
	v_mfma_f32_16x16x32_bf16 v[74:77], v[134:137], v[190:193], v[74:77]
	s_setprio 0
	s_setprio 1
	v_mfma_f32_16x16x32_bf16 v[126:129], v[138:141], v[162:165], v[126:129]
	v_mfma_f32_16x16x32_bf16 v[122:125], v[146:149], v[162:165], v[122:125]
	v_mfma_f32_16x16x32_bf16 v[102:105], v[138:141], v[170:173], v[102:105]
	v_mfma_f32_16x16x32_bf16 v[98:101], v[146:149], v[170:173], v[98:101]
	v_mfma_f32_16x16x32_bf16 v[86:89], v[138:141], v[178:181], v[86:89]
	v_mfma_f32_16x16x32_bf16 v[82:85], v[146:149], v[178:181], v[82:85]
	v_mfma_f32_16x16x32_bf16 v[70:73], v[138:141], v[186:189], v[70:73]
	v_mfma_f32_16x16x32_bf16 v[66:69], v[146:149], v[186:189], v[66:69]
	v_mfma_f32_16x16x32_bf16 v[126:129], v[142:145], v[166:169], v[126:129]
	v_mfma_f32_16x16x32_bf16 v[122:125], v[150:153], v[166:169], v[122:125]
	v_mfma_f32_16x16x32_bf16 v[102:105], v[142:145], v[174:177], v[102:105]
	v_mfma_f32_16x16x32_bf16 v[98:101], v[150:153], v[174:177], v[98:101]
	v_mfma_f32_16x16x32_bf16 v[86:89], v[142:145], v[182:185], v[86:89]
	v_mfma_f32_16x16x32_bf16 v[82:85], v[150:153], v[182:185], v[82:85]
	v_mfma_f32_16x16x32_bf16 v[70:73], v[142:145], v[190:193], v[70:73]
	v_mfma_f32_16x16x32_bf16 v[66:69], v[150:153], v[190:193], v[66:69]
	s_setprio 0
	s_barrier
	s_add_i32 s85, s85, s69
	s_mov_b32 m0, s85
	s_nop 0
	global_load_lds_dwordx4 v208, s[52:53]
	ds_read_b128 v[162:165], v244 offset:16384
	ds_read_b128 v[166:169], v244 offset:17408
	s_add_i32 m0, s85, 0x2000
	s_add_u32 s88, s52, 0x80000
	s_addc_u32 s89, s53, 0
	s_add_i32 s85, s92, s69
	global_load_lds_dwordx4 v212, s[52:53]
	ds_read_b128 v[170:173], v244 offset:18432
	ds_read_b128 v[174:177], v244 offset:19456
	s_mov_b32 m0, s85
	s_nop 0
	global_load_lds_dwordx4 v208, s[88:89]
	ds_read_b128 v[178:181], v244 offset:20480
	ds_read_b128 v[182:185], v244 offset:21504
	s_add_i32 m0, s85, 0x2000
	s_nop 0
	global_load_lds_dwordx4 v212, s[88:89]
	ds_read_b128 v[186:189], v244 offset:22528
	ds_read_b128 v[190:193], v244 offset:23552
	s_mov_b32 m0, s70
	s_nop 0
	global_load_lds_dwordx4 v206, s[82:83]
	s_mov_b32 m0, s71
	s_nop 0
	global_load_lds_dwordx4 v210, s[82:83]
	s_waitcnt vmcnt(8)
	s_waitcnt lgkmcnt(0)
	s_barrier
	s_setprio 1
	s_waitcnt lgkmcnt(0)
	v_mfma_f32_16x16x32_bf16 v[62:65], v[114:117], v[162:165], v[62:65]
	v_mfma_f32_16x16x32_bf16 v[58:61], v[130:133], v[162:165], v[58:61]
	v_mfma_f32_16x16x32_bf16 v[46:49], v[114:117], v[170:173], v[46:49]
	v_mfma_f32_16x16x32_bf16 v[42:45], v[130:133], v[170:173], v[42:45]
	v_mfma_f32_16x16x32_bf16 v[30:33], v[114:117], v[178:181], v[30:33]
	v_mfma_f32_16x16x32_bf16 v[26:29], v[130:133], v[178:181], v[26:29]
	v_mfma_f32_16x16x32_bf16 v[14:17], v[114:117], v[186:189], v[14:17]
	v_mfma_f32_16x16x32_bf16 v[10:13], v[130:133], v[186:189], v[10:13]
	v_mfma_f32_16x16x32_bf16 v[62:65], v[118:121], v[166:169], v[62:65]
	v_mfma_f32_16x16x32_bf16 v[58:61], v[134:137], v[166:169], v[58:61]
	v_mfma_f32_16x16x32_bf16 v[46:49], v[118:121], v[174:177], v[46:49]
	v_mfma_f32_16x16x32_bf16 v[42:45], v[134:137], v[174:177], v[42:45]
	v_mfma_f32_16x16x32_bf16 v[30:33], v[118:121], v[182:185], v[30:33]
	v_mfma_f32_16x16x32_bf16 v[26:29], v[134:137], v[182:185], v[26:29]
	v_mfma_f32_16x16x32_bf16 v[14:17], v[118:121], v[190:193], v[14:17]
	v_mfma_f32_16x16x32_bf16 v[10:13], v[134:137], v[190:193], v[10:13]
	s_setprio 0
	s_setprio 1
	v_mfma_f32_16x16x32_bf16 v[54:57], v[138:141], v[162:165], v[54:57]
	v_mfma_f32_16x16x32_bf16 v[50:53], v[146:149], v[162:165], v[50:53]
	v_mfma_f32_16x16x32_bf16 v[38:41], v[138:141], v[170:173], v[38:41]
	v_mfma_f32_16x16x32_bf16 v[34:37], v[146:149], v[170:173], v[34:37]
	v_mfma_f32_16x16x32_bf16 v[22:25], v[138:141], v[178:181], v[22:25]
	v_mfma_f32_16x16x32_bf16 v[18:21], v[146:149], v[178:181], v[18:21]
	v_mfma_f32_16x16x32_bf16 v[6:9], v[138:141], v[186:189], v[6:9]
	v_mfma_f32_16x16x32_bf16 v[2:5], v[146:149], v[186:189], v[2:5]
	v_mfma_f32_16x16x32_bf16 v[54:57], v[142:145], v[166:169], v[54:57]
	v_mfma_f32_16x16x32_bf16 v[50:53], v[150:153], v[166:169], v[50:53]
	v_mfma_f32_16x16x32_bf16 v[38:41], v[142:145], v[174:177], v[38:41]
	v_mfma_f32_16x16x32_bf16 v[34:37], v[150:153], v[174:177], v[34:37]
	v_mfma_f32_16x16x32_bf16 v[22:25], v[142:145], v[182:185], v[22:25]
	v_mfma_f32_16x16x32_bf16 v[18:21], v[150:153], v[182:185], v[18:21]
	v_mfma_f32_16x16x32_bf16 v[6:9], v[142:145], v[190:193], v[6:9]
	v_mfma_f32_16x16x32_bf16 v[2:5], v[150:153], v[190:193], v[2:5]
	s_setprio 0
	s_barrier
; #define PG8_STAGE(bufoff, gbase, voff) do { _Pragma("unroll") for (int _i = 0; _i < 2; ++_i) \
;         __builtin_amdgcn_global_load_lds((const unsigned*)((const char*)(gbase) + (voff)[_i]), (PG8_LAS unsigned*)(lds + (bufoff) + ldsw + _i * 8192), 16, 0, 0); } while (0)
; #define PG8_LDA(dst, b, h) do { _Pragma("unroll") for (int m = 0; m < 4; ++m) _Pragma("unroll") for (int k = 0; k < 2; ++k) dst[m][k] = *(const PG8_LAS bf16x8*)(lds + PG8_SA(b, h) + aoff + m * 2048 + k * 1024); } while (0)
; #define PG8_LDB(dst, b, h) do { _Pragma("unroll") for (int n = 0; n < 2; ++n) _Pragma("unroll") for (int k = 0; k < 2; ++k) dst[n][k] = *(const PG8_LAS bf16x8*)(lds + PG8_SB(b, h) + boff + n * 2048 + k * 1024); } while (0)
; #define PG8_MMA(ai, bj, At, Bt) do { __builtin_amdgcn_s_setprio(1); _Pragma("unroll") for (int m = 0; m < 4; ++m) _Pragma("unroll") for (int n = 0; n < 2; ++n) _Pragma("unroll") for (int k = 0; k < 2; ++k) \
;         acc[ai][bj][m][n] = __builtin_amdgcn_mfma_f32_16x16x32_bf16(Bt[n][k], At[m][k], acc[ai][bj][m][n], 0, 0, 0); __builtin_amdgcn_s_setprio(0); } while (0)
; #define PG8_WAIT_V(n) asm volatile("s_waitcnt vmcnt(" #n ")" ::: "memory")
; #define PG8_WAIT_L(n) asm volatile("s_waitcnt lgkmcnt(" #n ")" ::: "memory")
; #define PG8_BAR __builtin_amdgcn_s_barrier()
; #define PG8_SCHED __builtin_amdgcn_sched_barrier(0)
; template <class Epi, class Sched, bool ALIGN_EPI = false, bool SP2 = false>
; __device__ __forceinline__ void gemm_phase(PG8_LAS unsigned char* lds, const Gemm g, const Sched& S, const Epi& E, const int wave_id) {
;     ...
;             PG8_LDB(B0, 1, 0); PG8_LDB(B1, 1, 1); PG8_SCHED; PG8_LDA(At, 1, 0); PG8_STAGE(PG8_SA(0, 1), a2 + hstep, voffA);
;             PG8_WAIT_V(8); PG8_WAIT_L(0); PG8_BAR; PG8_MMA(0, 0, At, B0); PG8_MMA(0, 1, At, B1); PG8_BAR; PG8_SCHED;
;             PG8_LDA(At, 1, 1); PG8_STAGE(PG8_SB(1, 0), b3, voffB); PG8_STAGE(PG8_SB(1, 1), b3 + hstep, voffB); PG8_STAGE(PG8_SA(1, 0), a3, voffA);
;             PG8_WAIT_V(8); PG8_WAIT_L(0); PG8_BAR; PG8_MMA(1, 0, At, B0); PG8_MMA(1, 1, At, B1); PG8_BAR; PG8_SCHED;
;     ...
;         if constexpr (ALIGN_EPI) { if (wr == 0) PG8_BAR; }
	s_add_i32 s85, 0, 0x18000
	s_add_i32 s88, 0, 0x1c000
	s_add_u32 s82, s82, 0x80000
	s_addc_u32 s83, s83, 0
	s_mov_b32 m0, s72
	s_nop 0
	global_load_lds_dwordx4 v206, s[82:83]
	ds_read_b128 v[114:117], v226 offset:32768
	ds_read_b128 v[118:121], v226 offset:33792
	ds_read_b128 v[130:133], v226 offset:34816
	ds_read_b128 v[134:137], v226 offset:35840
	ds_read_b128 v[138:141], v226 offset:49152
	ds_read_b128 v[142:145], v226 offset:50176
	ds_read_b128 v[146:149], v226 offset:51200
	ds_read_b128 v[150:153], v226 offset:52224
	s_mov_b32 m0, s73
	s_nop 0
	global_load_lds_dwordx4 v210, s[82:83]
	ds_read_b128 v[162:165], v244 offset:32768
	ds_read_b128 v[166:169], v244 offset:33792
	ds_read_b128 v[170:173], v244 offset:34816
	ds_read_b128 v[174:177], v244 offset:35840
	ds_read_b128 v[178:181], v244 offset:36864
	ds_read_b128 v[182:185], v244 offset:37888
	ds_read_b128 v[186:189], v244 offset:38912
	ds_read_b128 v[190:193], v244 offset:39936
	s_waitcnt vmcnt(8)
	s_waitcnt lgkmcnt(0)
	s_barrier
	s_setprio 1
	s_waitcnt lgkmcnt(0)
	v_mfma_f32_16x16x32_bf16 v[158:161], v[114:117], v[162:165], v[158:161]
	v_mfma_f32_16x16x32_bf16 v[154:157], v[130:133], v[162:165], v[154:157]
	v_mfma_f32_16x16x32_bf16 v[110:113], v[114:117], v[170:173], v[110:113]
	v_mfma_f32_16x16x32_bf16 v[106:109], v[130:133], v[170:173], v[106:109]
	v_mfma_f32_16x16x32_bf16 v[94:97], v[114:117], v[178:181], v[94:97]
	v_mfma_f32_16x16x32_bf16 v[90:93], v[130:133], v[178:181], v[90:93]
	v_mfma_f32_16x16x32_bf16 v[78:81], v[114:117], v[186:189], v[78:81]
	v_mfma_f32_16x16x32_bf16 v[74:77], v[130:133], v[186:189], v[74:77]
	v_mfma_f32_16x16x32_bf16 v[158:161], v[118:121], v[166:169], v[158:161]
	v_mfma_f32_16x16x32_bf16 v[154:157], v[134:137], v[166:169], v[154:157]
	v_mfma_f32_16x16x32_bf16 v[110:113], v[118:121], v[174:177], v[110:113]
	v_mfma_f32_16x16x32_bf16 v[106:109], v[134:137], v[174:177], v[106:109]
	v_mfma_f32_16x16x32_bf16 v[94:97], v[118:121], v[182:185], v[94:97]
	v_mfma_f32_16x16x32_bf16 v[90:93], v[134:137], v[182:185], v[90:93]
	v_mfma_f32_16x16x32_bf16 v[78:81], v[118:121], v[190:193], v[78:81]
	v_mfma_f32_16x16x32_bf16 v[74:77], v[134:137], v[190:193], v[74:77]
	s_setprio 0
	s_setprio 1
	v_mfma_f32_16x16x32_bf16 v[126:129], v[138:141], v[162:165], v[126:129]
	v_mfma_f32_16x16x32_bf16 v[122:125], v[146:149], v[162:165], v[122:125]
	v_mfma_f32_16x16x32_bf16 v[102:105], v[138:141], v[170:173], v[102:105]
	v_mfma_f32_16x16x32_bf16 v[98:101], v[146:149], v[170:173], v[98:101]
	v_mfma_f32_16x16x32_bf16 v[86:89], v[138:141], v[178:181], v[86:89]
	v_mfma_f32_16x16x32_bf16 v[82:85], v[146:149], v[178:181], v[82:85]
	v_mfma_f32_16x16x32_bf16 v[70:73], v[138:141], v[186:189], v[70:73]
	v_mfma_f32_16x16x32_bf16 v[66:69], v[146:149], v[186:189], v[66:69]
	v_mfma_f32_16x16x32_bf16 v[126:129], v[142:145], v[166:169], v[126:129]
	v_mfma_f32_16x16x32_bf16 v[122:125], v[150:153], v[166:169], v[122:125]
	v_mfma_f32_16x16x32_bf16 v[102:105], v[142:145], v[174:177], v[102:105]
	v_mfma_f32_16x16x32_bf16 v[98:101], v[150:153], v[174:177], v[98:101]
	v_mfma_f32_16x16x32_bf16 v[86:89], v[142:145], v[182:185], v[86:89]
	v_mfma_f32_16x16x32_bf16 v[82:85], v[150:153], v[182:185], v[82:85]
	v_mfma_f32_16x16x32_bf16 v[70:73], v[142:145], v[190:193], v[70:73]
	v_mfma_f32_16x16x32_bf16 v[66:69], v[150:153], v[190:193], v[66:69]
	s_setprio 0
	s_barrier
	s_add_u32 vcc_lo, s82, 0xfff80080
	s_addc_u32 vcc_hi, s83, -1
	s_mov_b32 m0, s76
	s_nop 0
	global_load_lds_dwordx4 v206, vcc
	ds_read_b128 v[162:165], v244 offset:49152
	ds_read_b128 v[166:169], v244 offset:50176
	s_mov_b32 m0, s77
	s_add_i32 s82, s85, s69
	global_load_lds_dwordx4 v210, vcc
	ds_read_b128 v[170:173], v244 offset:51200
	ds_read_b128 v[174:177], v244 offset:52224
	s_add_u32 vcc_lo, s52, 0x80
	s_addc_u32 vcc_hi, s53, 0
	s_mov_b32 m0, s82
	s_nop 0
	global_load_lds_dwordx4 v208, vcc
	ds_read_b128 v[178:181], v244 offset:53248
	ds_read_b128 v[182:185], v244 offset:54272
	s_add_i32 m0, s82, 0x2000
	s_add_u32 s52, s52, 0x80080
	s_addc_u32 s53, s53, 0
	global_load_lds_dwordx4 v212, vcc
	ds_read_b128 v[186:189], v244 offset:55296
	ds_read_b128 v[190:193], v244 offset:56320
	s_add_i32 s82, s88, s69
	s_mov_b32 m0, s82
	s_nop 0
	global_load_lds_dwordx4 v208, s[52:53]
	s_add_i32 m0, s82, 0x2000
	s_nop 0
	global_load_lds_dwordx4 v212, s[52:53]
	s_waitcnt vmcnt(8)
	s_waitcnt lgkmcnt(0)
	s_barrier
	s_setprio 1
	s_waitcnt lgkmcnt(0)
	v_mfma_f32_16x16x32_bf16 v[62:65], v[114:117], v[162:165], v[62:65]
	v_mfma_f32_16x16x32_bf16 v[58:61], v[130:133], v[162:165], v[58:61]
	v_mfma_f32_16x16x32_bf16 v[46:49], v[114:117], v[170:173], v[46:49]
	v_mfma_f32_16x16x32_bf16 v[42:45], v[130:133], v[170:173], v[42:45]
	v_mfma_f32_16x16x32_bf16 v[30:33], v[114:117], v[178:181], v[30:33]
	v_mfma_f32_16x16x32_bf16 v[26:29], v[130:133], v[178:181], v[26:29]
	v_mfma_f32_16x16x32_bf16 v[14:17], v[114:117], v[186:189], v[14:17]
	v_mfma_f32_16x16x32_bf16 v[10:13], v[130:133], v[186:189], v[10:13]
	v_mfma_f32_16x16x32_bf16 v[62:65], v[118:121], v[166:169], v[62:65]
	v_mfma_f32_16x16x32_bf16 v[58:61], v[134:137], v[166:169], v[58:61]
	v_mfma_f32_16x16x32_bf16 v[46:49], v[118:121], v[174:177], v[46:49]
	v_mfma_f32_16x16x32_bf16 v[42:45], v[134:137], v[174:177], v[42:45]
	v_mfma_f32_16x16x32_bf16 v[30:33], v[118:121], v[182:185], v[30:33]
	v_mfma_f32_16x16x32_bf16 v[26:29], v[134:137], v[182:185], v[26:29]
	v_mfma_f32_16x16x32_bf16 v[14:17], v[118:121], v[190:193], v[14:17]
	v_mfma_f32_16x16x32_bf16 v[10:13], v[134:137], v[190:193], v[10:13]
	s_setprio 0
	s_setprio 1
	v_mfma_f32_16x16x32_bf16 v[54:57], v[138:141], v[162:165], v[54:57]
	v_mfma_f32_16x16x32_bf16 v[50:53], v[146:149], v[162:165], v[50:53]
	v_mfma_f32_16x16x32_bf16 v[38:41], v[138:141], v[170:173], v[38:41]
	v_mfma_f32_16x16x32_bf16 v[34:37], v[146:149], v[170:173], v[34:37]
	v_mfma_f32_16x16x32_bf16 v[22:25], v[138:141], v[178:181], v[22:25]
	v_mfma_f32_16x16x32_bf16 v[18:21], v[146:149], v[178:181], v[18:21]
	v_mfma_f32_16x16x32_bf16 v[6:9], v[138:141], v[186:189], v[6:9]
	v_mfma_f32_16x16x32_bf16 v[2:5], v[146:149], v[186:189], v[2:5]
	v_mfma_f32_16x16x32_bf16 v[54:57], v[142:145], v[166:169], v[54:57]
	v_mfma_f32_16x16x32_bf16 v[50:53], v[150:153], v[166:169], v[50:53]
	v_mfma_f32_16x16x32_bf16 v[38:41], v[142:145], v[174:177], v[38:41]
	v_mfma_f32_16x16x32_bf16 v[34:37], v[150:153], v[174:177], v[34:37]
	v_mfma_f32_16x16x32_bf16 v[22:25], v[142:145], v[182:185], v[22:25]
	v_mfma_f32_16x16x32_bf16 v[18:21], v[150:153], v[182:185], v[18:21]
	v_mfma_f32_16x16x32_bf16 v[6:9], v[142:145], v[190:193], v[6:9]
	v_mfma_f32_16x16x32_bf16 v[2:5], v[150:153], v[190:193], v[2:5]
	s_setprio 0
	s_barrier
	s_add_i32 s84, s84, 2
	s_add_u32 s46, s46, 0x100
	s_addc_u32 s47, s47, 0
	s_add_u32 s80, s80, 0x100
	s_addc_u32 s81, s81, 0
	s_cmp_gt_u32 s84, 29
	s_cbranch_scc0 .LBB0_904
	s_and_b64 vcc, exec, s[16:17]
	s_mov_b32 s50, 0x90000
	s_mov_b32 s51, 0xa0000
	s_mov_b32 s82, 0xb0000
	s_cbranch_vccz .LBB0_907
	s_barrier
